# v18: v12 + removed the no-op setprio 0/1 pair between the two MFMA blocks of each GEMM super-phase
# baseline (speedup 1.0000x reference)
; #define PG8_STAGE(bufoff, gbase, voff) do { _Pragma("unroll") for (int _i = 0; _i < 2; ++_i) \
;         __builtin_amdgcn_global_load_lds((const unsigned*)((const char*)(gbase) + (voff)[_i]), (PG8_LAS unsigned*)(lds + (bufoff) + ldsw + _i * 8192), 16, 0, 0); } while (0)
; #define PG8_LDA(dst, b, h) do { _Pragma("unroll") for (int m = 0; m < 4; ++m) _Pragma("unroll") for (int k = 0; k < 2; ++k) dst[m][k] = *(const PG8_LAS bf16x8*)(lds + PG8_SA(b, h) + aoff + m * 2048 + k * 1024); } while (0)
; #define PG8_LDB(dst, b, h) do { _Pragma("unroll") for (int n = 0; n < 2; ++n) _Pragma("unroll") for (int k = 0; k < 2; ++k) dst[n][k] = *(const PG8_LAS bf16x8*)(lds + PG8_SB(b, h) + boff + n * 2048 + k * 1024); } while (0)
; #define PG8_MMA(ai, bj, At, Bt) do { __builtin_amdgcn_s_setprio(1); _Pragma("unroll") for (int m = 0; m < 4; ++m) _Pragma("unroll") for (int n = 0; n < 2; ++n) _Pragma("unroll") for (int k = 0; k < 2; ++k) \
;         acc[ai][bj][m][n] = __builtin_amdgcn_mfma_f32_16x16x32_bf16(Bt[n][k], At[m][k], acc[ai][bj][m][n], 0, 0, 0); __builtin_amdgcn_s_setprio(0); } while (0)
; #define PG8_WAIT_V(n) asm volatile("s_waitcnt vmcnt(" #n ")" ::: "memory")
; #define PG8_WAIT_L(n) asm volatile("s_waitcnt lgkmcnt(" #n ")" ::: "memory")
; #define PG8_BAR __builtin_amdgcn_s_barrier()
; #define PG8_SCHED __builtin_amdgcn_sched_barrier(0)
; template <class Epi, class Sched, bool ALIGN_EPI = false, bool SP2 = false>
; __device__ __forceinline__ void gemm_phase(PG8_LAS unsigned char* lds, const Gemm g, const Sched& S, const Epi& E, const int wave_s) {
;     ...
;             if constexpr (SP2) {
;             PG8_LDB(B0, 0, 0); PG8_LDB(B1, 0, 1); PG8_SCHED; PG8_LDA(At, 0, 0); PG8_STAGE(PG8_SA(1, 1), a1 + hstep, voffA);
;             PG8_WAIT_V(8); PG8_WAIT_L(0); PG8_BAR; PG8_MMA(0, 0, At, B0); PG8_MMA(0, 1, At, B1); PG8_BAR; PG8_SCHED;
;             PG8_LDA(At, 0, 1); PG8_STAGE(PG8_SB(0, 0), b2, voffB); PG8_STAGE(PG8_SB(0, 1), b2 + hstep, voffB); PG8_STAGE(PG8_SA(0, 0), a2, voffA);
.LBB0_219:
	s_add_u32 s34, s30, 0xfffc0080
	s_addc_u32 s35, s31, -1
	s_add_i32 s45, 0, 0x10000
	s_cmp_eq_u32 s68, 12
	s_cselect_b32 s37, s5, s35
	s_cselect_b32 s36, s23, s34
	v_add_u32_e32 v0, s45, v180
	s_cselect_b32 s35, s21, s64
	s_cselect_b32 s34, s29, s55
	s_add_i32 s75, 0, 0x14000
	ds_read_b128 v[78:81], v0
	ds_read_b128 v[86:89], v0 offset:1024
	ds_read_b128 v[98:101], v0 offset:2048
	ds_read_b128 v[102:105], v0 offset:3072
	v_add_u32_e32 v0, s75, v180
	ds_read_b128 v[170:173], v0
	ds_read_b128 v[174:177], v0 offset:1024
	ds_read_b128 v[184:187], v0 offset:2048
	ds_read_b128 v[188:191], v0 offset:3072
	v_lshl_add_u64 v[230:231], s[30:31], 0, v[164:165]
	s_add_i32 m0, s47, 0xc000
	ds_read_b128 v[192:195], v182
	ds_read_b128 v[196:199], v182 offset:1024
	ds_read_b128 v[200:203], v182 offset:2048
	ds_read_b128 v[210:213], v182 offset:3072
	ds_read_b128 v[214:217], v182 offset:4096
	ds_read_b128 v[218:221], v182 offset:5120
	ds_read_b128 v[222:225], v182 offset:6144
	ds_read_b128 v[226:229], v182 offset:7168
	global_load_lds_dwordx4 v[230:231], off
	v_lshl_add_u64 v[230:231], s[30:31], 0, v[166:167]
	s_add_i32 m0, s47, 0xe000
	s_nop 0
	global_load_lds_dwordx4 v[230:231], off
	s_waitcnt vmcnt(8)
	s_waitcnt lgkmcnt(0)
	s_barrier
	s_setprio 1
	s_waitcnt lgkmcnt(0)
	v_mfma_f32_16x16x32_bf16 v[142:145], v[78:81], v[192:195], v[142:145]
	v_mfma_f32_16x16x32_bf16 v[138:141], v[98:101], v[192:195], v[138:141]
	v_mfma_f32_16x16x32_bf16 v[126:129], v[78:81], v[200:203], v[126:129]
	v_mfma_f32_16x16x32_bf16 v[122:125], v[98:101], v[200:203], v[122:125]
	v_mfma_f32_16x16x32_bf16 v[110:113], v[78:81], v[214:217], v[110:113]
	v_mfma_f32_16x16x32_bf16 v[106:109], v[98:101], v[214:217], v[106:109]
	v_mfma_f32_16x16x32_bf16 v[82:85], v[78:81], v[222:225], v[82:85]
	v_mfma_f32_16x16x32_bf16 v[74:77], v[98:101], v[222:225], v[74:77]
	v_mfma_f32_16x16x32_bf16 v[142:145], v[86:89], v[196:199], v[142:145]
	v_mfma_f32_16x16x32_bf16 v[138:141], v[102:105], v[196:199], v[138:141]
	v_mfma_f32_16x16x32_bf16 v[126:129], v[86:89], v[210:213], v[126:129]
	v_mfma_f32_16x16x32_bf16 v[122:125], v[102:105], v[210:213], v[122:125]
	v_mfma_f32_16x16x32_bf16 v[110:113], v[86:89], v[218:221], v[110:113]
	v_mfma_f32_16x16x32_bf16 v[106:109], v[102:105], v[218:221], v[106:109]
	v_mfma_f32_16x16x32_bf16 v[82:85], v[86:89], v[226:229], v[82:85]
	v_mfma_f32_16x16x32_bf16 v[74:77], v[102:105], v[226:229], v[74:77]
	v_mfma_f32_16x16x32_bf16 v[134:137], v[170:173], v[192:195], v[134:137]
	v_mfma_f32_16x16x32_bf16 v[130:133], v[184:187], v[192:195], v[130:133]
	v_mfma_f32_16x16x32_bf16 v[118:121], v[170:173], v[200:203], v[118:121]
	v_mfma_f32_16x16x32_bf16 v[114:117], v[184:187], v[200:203], v[114:117]
	v_mfma_f32_16x16x32_bf16 v[94:97], v[170:173], v[214:217], v[94:97]
	v_mfma_f32_16x16x32_bf16 v[90:93], v[184:187], v[214:217], v[90:93]
	v_mfma_f32_16x16x32_bf16 v[70:73], v[170:173], v[222:225], v[70:73]
	v_mfma_f32_16x16x32_bf16 v[66:69], v[184:187], v[222:225], v[66:69]
	v_mfma_f32_16x16x32_bf16 v[134:137], v[174:177], v[196:199], v[134:137]
	v_mfma_f32_16x16x32_bf16 v[130:133], v[188:191], v[196:199], v[130:133]
	v_mfma_f32_16x16x32_bf16 v[118:121], v[174:177], v[210:213], v[118:121]
	v_mfma_f32_16x16x32_bf16 v[114:117], v[188:191], v[210:213], v[114:117]
	v_mfma_f32_16x16x32_bf16 v[94:97], v[174:177], v[218:221], v[94:97]
	v_mfma_f32_16x16x32_bf16 v[90:93], v[188:191], v[218:221], v[90:93]
	v_mfma_f32_16x16x32_bf16 v[70:73], v[174:177], v[226:229], v[70:73]
	v_mfma_f32_16x16x32_bf16 v[66:69], v[188:191], v[226:229], v[66:69]
	s_setprio 0
	s_barrier
	s_add_i32 s45, s45, s44
	v_lshl_add_u64 v[230:231], s[34:35], 0, v[148:149]
	s_mov_b32 m0, s45
	ds_read_b128 v[192:195], v182 offset:16384
	ds_read_b128 v[196:199], v182 offset:17408
	ds_read_b128 v[200:203], v182 offset:18432
	ds_read_b128 v[210:213], v182 offset:19456
	ds_read_b128 v[214:217], v182 offset:20480
	ds_read_b128 v[218:221], v182 offset:21504
	ds_read_b128 v[222:225], v182 offset:22528
	ds_read_b128 v[226:229], v182 offset:23552
	global_load_lds_dwordx4 v[230:231], off
	s_add_i32 m0, s45, 0x2000
	s_add_u32 s80, s34, 0x40000
	v_lshl_add_u64 v[232:233], s[34:35], 0, v[152:153]
	s_addc_u32 s81, s35, 0
	s_add_i32 s45, s75, s44
	global_load_lds_dwordx4 v[232:233], off
	v_lshl_add_u64 v[234:235], s[80:81], 0, v[148:149]
	s_mov_b32 m0, s45
	v_lshl_add_u64 v[236:237], s[36:37], 0, v[150:151]
	global_load_lds_dwordx4 v[234:235], off
	v_lshl_add_u64 v[234:235], s[80:81], 0, v[152:153]
	s_add_i32 m0, s45, 0x2000
	s_nop 0
	global_load_lds_dwordx4 v[234:235], off
	v_lshl_add_u64 v[234:235], s[36:37], 0, v[146:147]
	s_mov_b32 m0, s47
	s_nop 0
	global_load_lds_dwordx4 v[234:235], off
	s_mov_b32 m0, s48
	s_nop 0
	global_load_lds_dwordx4 v[236:237], off
	s_waitcnt vmcnt(8)
	s_waitcnt lgkmcnt(0)
	s_barrier
; #define PG8_STAGE(bufoff, gbase, voff) do { _Pragma("unroll") for (int _i = 0; _i < 2; ++_i) \
;         __builtin_amdgcn_global_load_lds((const unsigned*)((const char*)(gbase) + (voff)[_i]), (PG8_LAS unsigned*)(lds + (bufoff) + ldsw + _i * 8192), 16, 0, 0); } while (0)
; #define PG8_LDA(dst, b, h) do { _Pragma("unroll") for (int m = 0; m < 4; ++m) _Pragma("unroll") for (int k = 0; k < 2; ++k) dst[m][k] = *(const PG8_LAS bf16x8*)(lds + PG8_SA(b, h) + aoff + m * 2048 + k * 1024); } while (0)
; #define PG8_LDB(dst, b, h) do { _Pragma("unroll") for (int n = 0; n < 2; ++n) _Pragma("unroll") for (int k = 0; k < 2; ++k) dst[n][k] = *(const PG8_LAS bf16x8*)(lds + PG8_SB(b, h) + boff + n * 2048 + k * 1024); } while (0)
; #define PG8_MMA(ai, bj, At, Bt) do { __builtin_amdgcn_s_setprio(1); _Pragma("unroll") for (int m = 0; m < 4; ++m) _Pragma("unroll") for (int n = 0; n < 2; ++n) _Pragma("unroll") for (int k = 0; k < 2; ++k) \
;         acc[ai][bj][m][n] = __builtin_amdgcn_mfma_f32_16x16x32_bf16(Bt[n][k], At[m][k], acc[ai][bj][m][n], 0, 0, 0); __builtin_amdgcn_s_setprio(0); } while (0)
; #define PG8_WAIT_V(n) asm volatile("s_waitcnt vmcnt(" #n ")" ::: "memory")
; #define PG8_WAIT_L(n) asm volatile("s_waitcnt lgkmcnt(" #n ")" ::: "memory")
; #define PG8_BAR __builtin_amdgcn_s_barrier()
; #define PG8_SCHED __builtin_amdgcn_sched_barrier(0)
; template <class Epi, class Sched, bool ALIGN_EPI = false, bool SP2 = false>
; __device__ __forceinline__ void gemm_phase(PG8_LAS unsigned char* lds, const Gemm g, const Sched& S, const Epi& E, const int wave_s) {
;     ...
;             PG8_WAIT_V(8); PG8_WAIT_L(0); PG8_BAR; PG8_MMA(1, 0, At, B0); PG8_MMA(1, 1, At, B1); PG8_BAR; PG8_SCHED;
;             PG8_LDB(B0, 1, 0); PG8_LDB(B1, 1, 1); PG8_SCHED; PG8_LDA(At, 1, 0); PG8_STAGE(PG8_SA(0, 1), a2 + hstep, voffA);
;             PG8_WAIT_V(8); PG8_WAIT_L(0); PG8_BAR; PG8_MMA(0, 0, At, B0); PG8_MMA(0, 1, At, B1); PG8_BAR; PG8_SCHED;
	s_setprio 1
	s_waitcnt lgkmcnt(0)
	v_mfma_f32_16x16x32_bf16 v[62:65], v[78:81], v[192:195], v[62:65]
	v_mfma_f32_16x16x32_bf16 v[58:61], v[98:101], v[192:195], v[58:61]
	v_mfma_f32_16x16x32_bf16 v[46:49], v[78:81], v[200:203], v[46:49]
	v_mfma_f32_16x16x32_bf16 v[42:45], v[98:101], v[200:203], v[42:45]
	v_mfma_f32_16x16x32_bf16 v[30:33], v[78:81], v[214:217], v[30:33]
	v_mfma_f32_16x16x32_bf16 v[26:29], v[98:101], v[214:217], v[26:29]
	v_mfma_f32_16x16x32_bf16 v[14:17], v[78:81], v[222:225], v[14:17]
	v_mfma_f32_16x16x32_bf16 v[10:13], v[98:101], v[222:225], v[10:13]
	v_mfma_f32_16x16x32_bf16 v[62:65], v[86:89], v[196:199], v[62:65]
	v_mfma_f32_16x16x32_bf16 v[58:61], v[102:105], v[196:199], v[58:61]
	v_mfma_f32_16x16x32_bf16 v[46:49], v[86:89], v[210:213], v[46:49]
	v_mfma_f32_16x16x32_bf16 v[42:45], v[102:105], v[210:213], v[42:45]
	v_mfma_f32_16x16x32_bf16 v[30:33], v[86:89], v[218:221], v[30:33]
	v_mfma_f32_16x16x32_bf16 v[26:29], v[102:105], v[218:221], v[26:29]
	v_mfma_f32_16x16x32_bf16 v[14:17], v[86:89], v[226:229], v[14:17]
	v_mfma_f32_16x16x32_bf16 v[10:13], v[102:105], v[226:229], v[10:13]
	v_mfma_f32_16x16x32_bf16 v[54:57], v[170:173], v[192:195], v[54:57]
	v_mfma_f32_16x16x32_bf16 v[50:53], v[184:187], v[192:195], v[50:53]
	v_mfma_f32_16x16x32_bf16 v[38:41], v[170:173], v[200:203], v[38:41]
	v_mfma_f32_16x16x32_bf16 v[34:37], v[184:187], v[200:203], v[34:37]
	v_mfma_f32_16x16x32_bf16 v[22:25], v[170:173], v[214:217], v[22:25]
	v_mfma_f32_16x16x32_bf16 v[18:21], v[184:187], v[214:217], v[18:21]
	v_mfma_f32_16x16x32_bf16 v[6:9], v[170:173], v[222:225], v[6:9]
	v_mfma_f32_16x16x32_bf16 v[2:5], v[184:187], v[222:225], v[2:5]
	v_mfma_f32_16x16x32_bf16 v[54:57], v[174:177], v[196:199], v[54:57]
	v_mfma_f32_16x16x32_bf16 v[50:53], v[188:191], v[196:199], v[50:53]
	v_mfma_f32_16x16x32_bf16 v[38:41], v[174:177], v[210:213], v[38:41]
	v_mfma_f32_16x16x32_bf16 v[34:37], v[188:191], v[210:213], v[34:37]
	v_mfma_f32_16x16x32_bf16 v[22:25], v[174:177], v[218:221], v[22:25]
	v_mfma_f32_16x16x32_bf16 v[18:21], v[188:191], v[218:221], v[18:21]
	v_mfma_f32_16x16x32_bf16 v[6:9], v[174:177], v[226:229], v[6:9]
	v_mfma_f32_16x16x32_bf16 v[2:5], v[188:191], v[226:229], v[2:5]
	s_setprio 0
	s_barrier
	s_add_i32 s45, 0, 0x18000
	v_add_u32_e32 v0, s45, v180
	s_add_i32 s75, 0, 0x1c000
	ds_read_b128 v[78:81], v0
	ds_read_b128 v[86:89], v0 offset:1024
	ds_read_b128 v[98:101], v0 offset:2048
	ds_read_b128 v[102:105], v0 offset:3072
	v_add_u32_e32 v0, s75, v180
	ds_read_b128 v[170:173], v0
	ds_read_b128 v[174:177], v0 offset:1024
	ds_read_b128 v[184:187], v0 offset:2048
	ds_read_b128 v[188:191], v0 offset:3072
	s_add_u32 s36, s36, 0x40000
	s_addc_u32 s37, s37, 0
	s_mov_b32 m0, s49
	v_lshl_add_u64 v[238:239], s[36:37], 0, v[146:147]
	ds_read_b128 v[192:195], v182 offset:32768
	ds_read_b128 v[196:199], v182 offset:33792
	ds_read_b128 v[200:203], v182 offset:34816
	ds_read_b128 v[210:213], v182 offset:35840
	ds_read_b128 v[214:217], v182 offset:36864
	ds_read_b128 v[218:221], v182 offset:37888
	ds_read_b128 v[222:225], v182 offset:38912
	ds_read_b128 v[226:229], v182 offset:39936
	global_load_lds_dwordx4 v[238:239], off
	v_lshl_add_u64 v[238:239], s[36:37], 0, v[150:151]
	s_mov_b32 m0, s50
	s_nop 0
	global_load_lds_dwordx4 v[238:239], off
	s_waitcnt vmcnt(8)
	s_waitcnt lgkmcnt(0)
	s_barrier
	s_setprio 1
	s_waitcnt lgkmcnt(0)
	v_mfma_f32_16x16x32_bf16 v[142:145], v[78:81], v[192:195], v[142:145]
	v_mfma_f32_16x16x32_bf16 v[138:141], v[98:101], v[192:195], v[138:141]
	v_mfma_f32_16x16x32_bf16 v[126:129], v[78:81], v[200:203], v[126:129]
	v_mfma_f32_16x16x32_bf16 v[122:125], v[98:101], v[200:203], v[122:125]
	v_mfma_f32_16x16x32_bf16 v[110:113], v[78:81], v[214:217], v[110:113]
	v_mfma_f32_16x16x32_bf16 v[106:109], v[98:101], v[214:217], v[106:109]
	v_mfma_f32_16x16x32_bf16 v[82:85], v[78:81], v[222:225], v[82:85]
	v_mfma_f32_16x16x32_bf16 v[74:77], v[98:101], v[222:225], v[74:77]
	v_mfma_f32_16x16x32_bf16 v[142:145], v[86:89], v[196:199], v[142:145]
	v_mfma_f32_16x16x32_bf16 v[138:141], v[102:105], v[196:199], v[138:141]
	v_mfma_f32_16x16x32_bf16 v[126:129], v[86:89], v[210:213], v[126:129]
	v_mfma_f32_16x16x32_bf16 v[122:125], v[102:105], v[210:213], v[122:125]
	v_mfma_f32_16x16x32_bf16 v[110:113], v[86:89], v[218:221], v[110:113]
	v_mfma_f32_16x16x32_bf16 v[106:109], v[102:105], v[218:221], v[106:109]
	v_mfma_f32_16x16x32_bf16 v[82:85], v[86:89], v[226:229], v[82:85]
	v_mfma_f32_16x16x32_bf16 v[74:77], v[102:105], v[226:229], v[74:77]
	v_mfma_f32_16x16x32_bf16 v[134:137], v[170:173], v[192:195], v[134:137]
	v_mfma_f32_16x16x32_bf16 v[130:133], v[184:187], v[192:195], v[130:133]
	v_mfma_f32_16x16x32_bf16 v[118:121], v[170:173], v[200:203], v[118:121]
	v_mfma_f32_16x16x32_bf16 v[114:117], v[184:187], v[200:203], v[114:117]
	v_mfma_f32_16x16x32_bf16 v[94:97], v[170:173], v[214:217], v[94:97]
	v_mfma_f32_16x16x32_bf16 v[90:93], v[184:187], v[214:217], v[90:93]
	v_mfma_f32_16x16x32_bf16 v[70:73], v[170:173], v[222:225], v[70:73]
	v_mfma_f32_16x16x32_bf16 v[66:69], v[184:187], v[222:225], v[66:69]
	v_mfma_f32_16x16x32_bf16 v[134:137], v[174:177], v[196:199], v[134:137]
	v_mfma_f32_16x16x32_bf16 v[130:133], v[188:191], v[196:199], v[130:133]
	v_mfma_f32_16x16x32_bf16 v[118:121], v[174:177], v[210:213], v[118:121]
	v_mfma_f32_16x16x32_bf16 v[114:117], v[188:191], v[210:213], v[114:117]
	v_mfma_f32_16x16x32_bf16 v[94:97], v[174:177], v[218:221], v[94:97]
	v_mfma_f32_16x16x32_bf16 v[90:93], v[188:191], v[218:221], v[90:93]
	v_mfma_f32_16x16x32_bf16 v[70:73], v[174:177], v[226:229], v[70:73]
	v_mfma_f32_16x16x32_bf16 v[66:69], v[188:191], v[226:229], v[66:69]
	s_setprio 0
	s_barrier
; #define PG8_STAGE(bufoff, gbase, voff) do { _Pragma("unroll") for (int _i = 0; _i < 2; ++_i) \
;         __builtin_amdgcn_global_load_lds((const unsigned*)((const char*)(gbase) + (voff)[_i]), (PG8_LAS unsigned*)(lds + (bufoff) + ldsw + _i * 8192), 16, 0, 0); } while (0)
; #define PG8_LDA(dst, b, h) do { _Pragma("unroll") for (int m = 0; m < 4; ++m) _Pragma("unroll") for (int k = 0; k < 2; ++k) dst[m][k] = *(const PG8_LAS bf16x8*)(lds + PG8_SA(b, h) + aoff + m * 2048 + k * 1024); } while (0)
; #define PG8_MMA(ai, bj, At, Bt) do { __builtin_amdgcn_s_setprio(1); _Pragma("unroll") for (int m = 0; m < 4; ++m) _Pragma("unroll") for (int n = 0; n < 2; ++n) _Pragma("unroll") for (int k = 0; k < 2; ++k) \
;         acc[ai][bj][m][n] = __builtin_amdgcn_mfma_f32_16x16x32_bf16(Bt[n][k], At[m][k], acc[ai][bj][m][n], 0, 0, 0); __builtin_amdgcn_s_setprio(0); } while (0)
; #define PG8_WAIT_V(n) asm volatile("s_waitcnt vmcnt(" #n ")" ::: "memory")
; #define PG8_WAIT_L(n) asm volatile("s_waitcnt lgkmcnt(" #n ")" ::: "memory")
; #define PG8_BAR __builtin_amdgcn_s_barrier()
; #define PG8_SCHED __builtin_amdgcn_sched_barrier(0)
; template <class Epi, class Sched, bool ALIGN_EPI = false, bool SP2 = false>
; __device__ __forceinline__ void gemm_phase(PG8_LAS unsigned char* lds, const Gemm g, const Sched& S, const Epi& E, const int wave_s) {
;     ...
;         for (int t = 0; t < nt; t += 2) {
;             const bool last = (t == nt - 2);
;             const char* a1 = cA + (size_t)(t + 1) * kstep;
;             const char* a2 = last ? nA : cA + (size_t)(t + 2) * kstep; const char* b2 = last ? nB : cB + (size_t)(t + 2) * kstep;
;             const char* a3 = a2 + kstep; const char* b3 = b2 + kstep;
;             if (last && has_next) S.a_ready(nxt);
;     ...
;             PG8_LDA(At, 1, 1); PG8_STAGE(PG8_SB(1, 0), b3, voffB); PG8_STAGE(PG8_SB(1, 1), b3 + hstep, voffB); PG8_STAGE(PG8_SA(1, 0), a3, voffA);
;             PG8_WAIT_V(8); PG8_WAIT_L(0); PG8_BAR; PG8_MMA(1, 0, At, B0); PG8_MMA(1, 1, At, B1); PG8_BAR; PG8_SCHED;
	s_add_i32 s36, s45, s44
	v_lshl_add_u64 v[230:231], v[230:231], 0, s[70:71]
	s_mov_b32 m0, s36
	ds_read_b128 v[192:195], v182 offset:49152
	ds_read_b128 v[196:199], v182 offset:50176
	ds_read_b128 v[200:203], v182 offset:51200
	ds_read_b128 v[210:213], v182 offset:52224
	ds_read_b128 v[214:217], v182 offset:53248
	ds_read_b128 v[218:221], v182 offset:54272
	ds_read_b128 v[222:225], v182 offset:55296
	ds_read_b128 v[226:229], v182 offset:56320
	global_load_lds_dwordx4 v[230:231], off
	s_add_i32 m0, s36, 0x2000
	s_add_u32 s34, s34, 0x40080
	v_lshl_add_u64 v[230:231], v[232:233], 0, s[70:71]
	s_addc_u32 s35, s35, 0
	s_add_i32 s36, s75, s44
	global_load_lds_dwordx4 v[230:231], off
	v_lshl_add_u64 v[230:231], s[34:35], 0, v[148:149]
	s_mov_b32 m0, s36
	s_nop 0
	global_load_lds_dwordx4 v[230:231], off
	v_lshl_add_u64 v[230:231], s[34:35], 0, v[152:153]
	s_add_i32 m0, s36, 0x2000
	s_nop 0
	global_load_lds_dwordx4 v[230:231], off
	v_lshl_add_u64 v[230:231], v[234:235], 0, s[70:71]
	s_mov_b32 m0, s58
	s_nop 0
	global_load_lds_dwordx4 v[230:231], off
	v_lshl_add_u64 v[230:231], v[236:237], 0, s[70:71]
	s_mov_b32 m0, s59
	s_nop 0
	global_load_lds_dwordx4 v[230:231], off
	s_waitcnt vmcnt(8)
	s_waitcnt lgkmcnt(0)
	s_barrier
	s_setprio 1
	s_waitcnt lgkmcnt(0)
	v_mfma_f32_16x16x32_bf16 v[62:65], v[78:81], v[192:195], v[62:65]
	v_mfma_f32_16x16x32_bf16 v[58:61], v[98:101], v[192:195], v[58:61]
	v_mfma_f32_16x16x32_bf16 v[46:49], v[78:81], v[200:203], v[46:49]
	v_mfma_f32_16x16x32_bf16 v[42:45], v[98:101], v[200:203], v[42:45]
	v_mfma_f32_16x16x32_bf16 v[30:33], v[78:81], v[214:217], v[30:33]
	v_mfma_f32_16x16x32_bf16 v[26:29], v[98:101], v[214:217], v[26:29]
	v_mfma_f32_16x16x32_bf16 v[14:17], v[78:81], v[222:225], v[14:17]
	v_mfma_f32_16x16x32_bf16 v[10:13], v[98:101], v[222:225], v[10:13]
	v_mfma_f32_16x16x32_bf16 v[62:65], v[86:89], v[196:199], v[62:65]
	v_mfma_f32_16x16x32_bf16 v[58:61], v[102:105], v[196:199], v[58:61]
	v_mfma_f32_16x16x32_bf16 v[46:49], v[86:89], v[210:213], v[46:49]
	v_mfma_f32_16x16x32_bf16 v[42:45], v[102:105], v[210:213], v[42:45]
	v_mfma_f32_16x16x32_bf16 v[30:33], v[86:89], v[218:221], v[30:33]
	v_mfma_f32_16x16x32_bf16 v[26:29], v[102:105], v[218:221], v[26:29]
	v_mfma_f32_16x16x32_bf16 v[14:17], v[86:89], v[226:229], v[14:17]
	v_mfma_f32_16x16x32_bf16 v[10:13], v[102:105], v[226:229], v[10:13]
	v_mfma_f32_16x16x32_bf16 v[54:57], v[170:173], v[192:195], v[54:57]
	v_mfma_f32_16x16x32_bf16 v[50:53], v[184:187], v[192:195], v[50:53]
	v_mfma_f32_16x16x32_bf16 v[38:41], v[170:173], v[200:203], v[38:41]
	v_mfma_f32_16x16x32_bf16 v[34:37], v[184:187], v[200:203], v[34:37]
	v_mfma_f32_16x16x32_bf16 v[22:25], v[170:173], v[214:217], v[22:25]
	v_mfma_f32_16x16x32_bf16 v[18:21], v[184:187], v[214:217], v[18:21]
	v_mfma_f32_16x16x32_bf16 v[6:9], v[170:173], v[222:225], v[6:9]
	v_mfma_f32_16x16x32_bf16 v[2:5], v[184:187], v[222:225], v[2:5]
	v_mfma_f32_16x16x32_bf16 v[54:57], v[174:177], v[196:199], v[54:57]
	v_mfma_f32_16x16x32_bf16 v[50:53], v[188:191], v[196:199], v[50:53]
	v_mfma_f32_16x16x32_bf16 v[38:41], v[174:177], v[210:213], v[38:41]
	v_mfma_f32_16x16x32_bf16 v[34:37], v[188:191], v[210:213], v[34:37]
	v_mfma_f32_16x16x32_bf16 v[22:25], v[174:177], v[218:221], v[22:25]
	v_mfma_f32_16x16x32_bf16 v[18:21], v[188:191], v[218:221], v[18:21]
	v_mfma_f32_16x16x32_bf16 v[6:9], v[174:177], v[226:229], v[6:9]
	v_mfma_f32_16x16x32_bf16 v[2:5], v[188:191], v[226:229], v[2:5]
	s_setprio 0
	s_barrier
	s_add_i32 s68, s68, 2
	s_add_u32 s30, s30, 0x100
	s_addc_u32 s31, s31, 0
	s_add_u32 s55, s55, 0x100
	s_addc_u32 s64, s64, 0
	s_cmp_gt_u32 s68, 13
	s_cbranch_scc0 .LBB0_219
	s_and_b64 vcc, exec, s[18:19]
	s_cbranch_vccz .LBB0_222
	s_barrier

; #define PG8_STAGE(bufoff, gbase, voff) do { _Pragma("unroll") for (int _i = 0; _i < 2; ++_i) \
;         __builtin_amdgcn_global_load_lds((const unsigned*)((const char*)(gbase) + (voff)[_i]), (PG8_LAS unsigned*)(lds + (bufoff) + ldsw + _i * 8192), 16, 0, 0); } while (0)
; #define PG8_LDA(dst, b, h) do { _Pragma("unroll") for (int m = 0; m < 4; ++m) _Pragma("unroll") for (int k = 0; k < 2; ++k) dst[m][k] = *(const PG8_LAS bf16x8*)(lds + PG8_SA(b, h) + aoff + m * 2048 + k * 1024); } while (0)
; #define PG8_LDB(dst, b, h) do { _Pragma("unroll") for (int n = 0; n < 2; ++n) _Pragma("unroll") for (int k = 0; k < 2; ++k) dst[n][k] = *(const PG8_LAS bf16x8*)(lds + PG8_SB(b, h) + boff + n * 2048 + k * 1024); } while (0)
; #define PG8_MMA(ai, bj, At, Bt) do { __builtin_amdgcn_s_setprio(1); _Pragma("unroll") for (int m = 0; m < 4; ++m) _Pragma("unroll") for (int n = 0; n < 2; ++n) _Pragma("unroll") for (int k = 0; k < 2; ++k) \
;         acc[ai][bj][m][n] = __builtin_amdgcn_mfma_f32_16x16x32_bf16(Bt[n][k], At[m][k], acc[ai][bj][m][n], 0, 0, 0); __builtin_amdgcn_s_setprio(0); } while (0)
; #define PG8_WAIT_V(n) asm volatile("s_waitcnt vmcnt(" #n ")" ::: "memory")
; #define PG8_WAIT_L(n) asm volatile("s_waitcnt lgkmcnt(" #n ")" ::: "memory")
; #define PG8_BAR __builtin_amdgcn_s_barrier()
; #define PG8_SCHED __builtin_amdgcn_sched_barrier(0)
; template <class Epi, class Sched, bool ALIGN_EPI = false, bool SP2 = false>
; __device__ __forceinline__ void gemm_phase(PG8_LAS unsigned char* lds, const Gemm g, const Sched& S, const Epi& E, const int wave_s) {
;     ...
;             if constexpr (SP2) {
;             PG8_LDB(B0, 0, 0); PG8_LDB(B1, 0, 1); PG8_SCHED; PG8_LDA(At, 0, 0); PG8_STAGE(PG8_SA(1, 1), a1 + hstep, voffA);
;             PG8_WAIT_V(8); PG8_WAIT_L(0); PG8_BAR; PG8_MMA(0, 0, At, B0); PG8_MMA(0, 1, At, B1); PG8_BAR; PG8_SCHED;
;             PG8_LDA(At, 0, 1); PG8_STAGE(PG8_SB(0, 0), b2, voffB); PG8_STAGE(PG8_SB(0, 1), b2 + hstep, voffB); PG8_STAGE(PG8_SA(0, 0), a2, voffA);
.LBB0_325:
	s_add_u32 s30, s28, 0xfffc0080
	s_addc_u32 s31, s29, -1
	s_add_i32 s45, 0, 0x10000
	s_cmp_eq_u32 s68, 12
	s_cselect_b32 s35, s19, s31
	s_cselect_b32 s34, s25, s30
	v_add_u32_e32 v0, s45, v181
	s_cselect_b32 s31, s17, s65
	s_cselect_b32 s30, s55, s64
	s_add_i32 s75, 0, 0x14000
	ds_read_b128 v[130:133], v0
	ds_read_b128 v[134:137], v0 offset:1024
	ds_read_b128 v[138:141], v0 offset:2048
	ds_read_b128 v[142:145], v0 offset:3072
	v_add_u32_e32 v0, s75, v181
	ds_read_b128 v[172:175], v0
	ds_read_b128 v[176:179], v0 offset:1024
	ds_read_b128 v[186:189], v0 offset:2048
	ds_read_b128 v[190:193], v0 offset:3072
	v_lshl_add_u64 v[202:203], s[28:29], 0, v[168:169]
	s_add_i32 m0, s27, 0xc000
	ds_read_b128 v[194:197], v185
	ds_read_b128 v[198:201], v185 offset:1024
	ds_read_b128 v[210:213], v185 offset:2048
	ds_read_b128 v[214:217], v185 offset:3072
	ds_read_b128 v[218:221], v185 offset:4096
	ds_read_b128 v[222:225], v185 offset:5120
	ds_read_b128 v[226:229], v185 offset:6144
	ds_read_b128 v[230:233], v185 offset:7168
	global_load_lds_dwordx4 v[202:203], off
	v_lshl_add_u64 v[202:203], s[28:29], 0, v[170:171]
	s_add_i32 m0, s27, 0xe000
	s_nop 0
	global_load_lds_dwordx4 v[202:203], off
	s_waitcnt vmcnt(8)
	s_waitcnt lgkmcnt(0)
	s_barrier
	s_setprio 1
	s_waitcnt lgkmcnt(0)
	v_mfma_f32_16x16x32_bf16 v[126:129], v[130:133], v[194:197], v[126:129]
	v_mfma_f32_16x16x32_bf16 v[122:125], v[138:141], v[194:197], v[122:125]
	v_mfma_f32_16x16x32_bf16 v[110:113], v[130:133], v[210:213], v[110:113]
	v_mfma_f32_16x16x32_bf16 v[106:109], v[138:141], v[210:213], v[106:109]
	v_mfma_f32_16x16x32_bf16 v[94:97], v[130:133], v[218:221], v[94:97]
	v_mfma_f32_16x16x32_bf16 v[90:93], v[138:141], v[218:221], v[90:93]
	v_mfma_f32_16x16x32_bf16 v[78:81], v[130:133], v[226:229], v[78:81]
	v_mfma_f32_16x16x32_bf16 v[74:77], v[138:141], v[226:229], v[74:77]
	v_mfma_f32_16x16x32_bf16 v[126:129], v[134:137], v[198:201], v[126:129]
	v_mfma_f32_16x16x32_bf16 v[122:125], v[142:145], v[198:201], v[122:125]
	v_mfma_f32_16x16x32_bf16 v[110:113], v[134:137], v[214:217], v[110:113]
	v_mfma_f32_16x16x32_bf16 v[106:109], v[142:145], v[214:217], v[106:109]
	v_mfma_f32_16x16x32_bf16 v[94:97], v[134:137], v[222:225], v[94:97]
	v_mfma_f32_16x16x32_bf16 v[90:93], v[142:145], v[222:225], v[90:93]
	v_mfma_f32_16x16x32_bf16 v[78:81], v[134:137], v[230:233], v[78:81]
	v_mfma_f32_16x16x32_bf16 v[74:77], v[142:145], v[230:233], v[74:77]
	v_mfma_f32_16x16x32_bf16 v[118:121], v[172:175], v[194:197], v[118:121]
	v_mfma_f32_16x16x32_bf16 v[114:117], v[186:189], v[194:197], v[114:117]
	v_mfma_f32_16x16x32_bf16 v[102:105], v[172:175], v[210:213], v[102:105]
	v_mfma_f32_16x16x32_bf16 v[98:101], v[186:189], v[210:213], v[98:101]
	v_mfma_f32_16x16x32_bf16 v[86:89], v[172:175], v[218:221], v[86:89]
	v_mfma_f32_16x16x32_bf16 v[82:85], v[186:189], v[218:221], v[82:85]
	v_mfma_f32_16x16x32_bf16 v[70:73], v[172:175], v[226:229], v[70:73]
	v_mfma_f32_16x16x32_bf16 v[66:69], v[186:189], v[226:229], v[66:69]
	v_mfma_f32_16x16x32_bf16 v[118:121], v[176:179], v[198:201], v[118:121]
	v_mfma_f32_16x16x32_bf16 v[114:117], v[190:193], v[198:201], v[114:117]
	v_mfma_f32_16x16x32_bf16 v[102:105], v[176:179], v[214:217], v[102:105]
	v_mfma_f32_16x16x32_bf16 v[98:101], v[190:193], v[214:217], v[98:101]
	v_mfma_f32_16x16x32_bf16 v[86:89], v[176:179], v[222:225], v[86:89]
	v_mfma_f32_16x16x32_bf16 v[82:85], v[190:193], v[222:225], v[82:85]
	v_mfma_f32_16x16x32_bf16 v[70:73], v[176:179], v[230:233], v[70:73]
	v_mfma_f32_16x16x32_bf16 v[66:69], v[190:193], v[230:233], v[66:69]
	s_setprio 0
	s_barrier
	s_add_i32 s45, s45, s44
	v_lshl_add_u64 v[202:203], s[30:31], 0, v[148:149]
	s_mov_b32 m0, s45
	ds_read_b128 v[194:197], v185 offset:16384
	ds_read_b128 v[198:201], v185 offset:17408
	ds_read_b128 v[210:213], v185 offset:18432
	ds_read_b128 v[214:217], v185 offset:19456
	ds_read_b128 v[218:221], v185 offset:20480
	ds_read_b128 v[222:225], v185 offset:21504
	ds_read_b128 v[226:229], v185 offset:22528
	ds_read_b128 v[230:233], v185 offset:23552
	global_load_lds_dwordx4 v[202:203], off
	s_add_i32 m0, s45, 0x2000
	s_add_u32 s80, s30, 0x40000
	v_lshl_add_u64 v[234:235], s[30:31], 0, v[152:153]
	s_addc_u32 s81, s31, 0
	s_add_i32 s45, s75, s44
	global_load_lds_dwordx4 v[234:235], off
	v_lshl_add_u64 v[236:237], s[80:81], 0, v[148:149]
	s_mov_b32 m0, s45
	v_lshl_add_u64 v[238:239], s[34:35], 0, v[150:151]
	global_load_lds_dwordx4 v[236:237], off
	v_lshl_add_u64 v[236:237], s[80:81], 0, v[152:153]
	s_add_i32 m0, s45, 0x2000
	s_nop 0
	global_load_lds_dwordx4 v[236:237], off
	v_lshl_add_u64 v[236:237], s[34:35], 0, v[146:147]
	s_mov_b32 m0, s27
	s_nop 0
	global_load_lds_dwordx4 v[236:237], off
	s_mov_b32 m0, s47
	s_nop 0
	global_load_lds_dwordx4 v[238:239], off
	s_waitcnt vmcnt(8)
	s_waitcnt lgkmcnt(0)
	s_barrier
; #define PG8_STAGE(bufoff, gbase, voff) do { _Pragma("unroll") for (int _i = 0; _i < 2; ++_i) \
;         __builtin_amdgcn_global_load_lds((const unsigned*)((const char*)(gbase) + (voff)[_i]), (PG8_LAS unsigned*)(lds + (bufoff) + ldsw + _i * 8192), 16, 0, 0); } while (0)
; #define PG8_LDA(dst, b, h) do { _Pragma("unroll") for (int m = 0; m < 4; ++m) _Pragma("unroll") for (int k = 0; k < 2; ++k) dst[m][k] = *(const PG8_LAS bf16x8*)(lds + PG8_SA(b, h) + aoff + m * 2048 + k * 1024); } while (0)
; #define PG8_LDB(dst, b, h) do { _Pragma("unroll") for (int n = 0; n < 2; ++n) _Pragma("unroll") for (int k = 0; k < 2; ++k) dst[n][k] = *(const PG8_LAS bf16x8*)(lds + PG8_SB(b, h) + boff + n * 2048 + k * 1024); } while (0)
; #define PG8_MMA(ai, bj, At, Bt) do { __builtin_amdgcn_s_setprio(1); _Pragma("unroll") for (int m = 0; m < 4; ++m) _Pragma("unroll") for (int n = 0; n < 2; ++n) _Pragma("unroll") for (int k = 0; k < 2; ++k) \
;         acc[ai][bj][m][n] = __builtin_amdgcn_mfma_f32_16x16x32_bf16(Bt[n][k], At[m][k], acc[ai][bj][m][n], 0, 0, 0); __builtin_amdgcn_s_setprio(0); } while (0)
; #define PG8_WAIT_V(n) asm volatile("s_waitcnt vmcnt(" #n ")" ::: "memory")
; #define PG8_WAIT_L(n) asm volatile("s_waitcnt lgkmcnt(" #n ")" ::: "memory")
; #define PG8_BAR __builtin_amdgcn_s_barrier()
; #define PG8_SCHED __builtin_amdgcn_sched_barrier(0)
; template <class Epi, class Sched, bool ALIGN_EPI = false, bool SP2 = false>
; __device__ __forceinline__ void gemm_phase(PG8_LAS unsigned char* lds, const Gemm g, const Sched& S, const Epi& E, const int wave_s) {
;     ...
;             PG8_WAIT_V(8); PG8_WAIT_L(0); PG8_BAR; PG8_MMA(1, 0, At, B0); PG8_MMA(1, 1, At, B1); PG8_BAR; PG8_SCHED;
;             PG8_LDB(B0, 1, 0); PG8_LDB(B1, 1, 1); PG8_SCHED; PG8_LDA(At, 1, 0); PG8_STAGE(PG8_SA(0, 1), a2 + hstep, voffA);
;             PG8_WAIT_V(8); PG8_WAIT_L(0); PG8_BAR; PG8_MMA(0, 0, At, B0); PG8_MMA(0, 1, At, B1); PG8_BAR; PG8_SCHED;
	s_setprio 1
	s_waitcnt lgkmcnt(0)
	v_mfma_f32_16x16x32_bf16 v[62:65], v[130:133], v[194:197], v[62:65]
	v_mfma_f32_16x16x32_bf16 v[58:61], v[138:141], v[194:197], v[58:61]
	v_mfma_f32_16x16x32_bf16 v[46:49], v[130:133], v[210:213], v[46:49]
	v_mfma_f32_16x16x32_bf16 v[42:45], v[138:141], v[210:213], v[42:45]
	v_mfma_f32_16x16x32_bf16 v[30:33], v[130:133], v[218:221], v[30:33]
	v_mfma_f32_16x16x32_bf16 v[26:29], v[138:141], v[218:221], v[26:29]
	v_mfma_f32_16x16x32_bf16 v[14:17], v[130:133], v[226:229], v[14:17]
	v_mfma_f32_16x16x32_bf16 v[10:13], v[138:141], v[226:229], v[10:13]
	v_mfma_f32_16x16x32_bf16 v[62:65], v[134:137], v[198:201], v[62:65]
	v_mfma_f32_16x16x32_bf16 v[58:61], v[142:145], v[198:201], v[58:61]
	v_mfma_f32_16x16x32_bf16 v[46:49], v[134:137], v[214:217], v[46:49]
	v_mfma_f32_16x16x32_bf16 v[42:45], v[142:145], v[214:217], v[42:45]
	v_mfma_f32_16x16x32_bf16 v[30:33], v[134:137], v[222:225], v[30:33]
	v_mfma_f32_16x16x32_bf16 v[26:29], v[142:145], v[222:225], v[26:29]
	v_mfma_f32_16x16x32_bf16 v[14:17], v[134:137], v[230:233], v[14:17]
	v_mfma_f32_16x16x32_bf16 v[10:13], v[142:145], v[230:233], v[10:13]
	v_mfma_f32_16x16x32_bf16 v[54:57], v[172:175], v[194:197], v[54:57]
	v_mfma_f32_16x16x32_bf16 v[50:53], v[186:189], v[194:197], v[50:53]
	v_mfma_f32_16x16x32_bf16 v[38:41], v[172:175], v[210:213], v[38:41]
	v_mfma_f32_16x16x32_bf16 v[34:37], v[186:189], v[210:213], v[34:37]
	v_mfma_f32_16x16x32_bf16 v[22:25], v[172:175], v[218:221], v[22:25]
	v_mfma_f32_16x16x32_bf16 v[18:21], v[186:189], v[218:221], v[18:21]
	v_mfma_f32_16x16x32_bf16 v[6:9], v[172:175], v[226:229], v[6:9]
	v_mfma_f32_16x16x32_bf16 v[2:5], v[186:189], v[226:229], v[2:5]
	v_mfma_f32_16x16x32_bf16 v[54:57], v[176:179], v[198:201], v[54:57]
	v_mfma_f32_16x16x32_bf16 v[50:53], v[190:193], v[198:201], v[50:53]
	v_mfma_f32_16x16x32_bf16 v[38:41], v[176:179], v[214:217], v[38:41]
	v_mfma_f32_16x16x32_bf16 v[34:37], v[190:193], v[214:217], v[34:37]
	v_mfma_f32_16x16x32_bf16 v[22:25], v[176:179], v[222:225], v[22:25]
	v_mfma_f32_16x16x32_bf16 v[18:21], v[190:193], v[222:225], v[18:21]
	v_mfma_f32_16x16x32_bf16 v[6:9], v[176:179], v[230:233], v[6:9]
	v_mfma_f32_16x16x32_bf16 v[2:5], v[190:193], v[230:233], v[2:5]
	s_setprio 0
	s_barrier
	s_add_i32 s45, 0, 0x18000
	v_add_u32_e32 v0, s45, v181
	s_add_i32 s75, 0, 0x1c000
	ds_read_b128 v[130:133], v0
	ds_read_b128 v[134:137], v0 offset:1024
	ds_read_b128 v[138:141], v0 offset:2048
	ds_read_b128 v[142:145], v0 offset:3072
	v_add_u32_e32 v0, s75, v181
	ds_read_b128 v[172:175], v0
	ds_read_b128 v[176:179], v0 offset:1024
	ds_read_b128 v[186:189], v0 offset:2048
	ds_read_b128 v[190:193], v0 offset:3072
	s_add_u32 s34, s34, 0x40000
	s_addc_u32 s35, s35, 0
	s_mov_b32 m0, s48
	v_lshl_add_u64 v[240:241], s[34:35], 0, v[146:147]
	ds_read_b128 v[194:197], v185 offset:32768
	ds_read_b128 v[198:201], v185 offset:33792
	ds_read_b128 v[210:213], v185 offset:34816
	ds_read_b128 v[214:217], v185 offset:35840
	ds_read_b128 v[218:221], v185 offset:36864
	ds_read_b128 v[222:225], v185 offset:37888
	ds_read_b128 v[226:229], v185 offset:38912
	ds_read_b128 v[230:233], v185 offset:39936
	global_load_lds_dwordx4 v[240:241], off
	v_lshl_add_u64 v[240:241], s[34:35], 0, v[150:151]
	s_mov_b32 m0, s49
	s_nop 0
	global_load_lds_dwordx4 v[240:241], off
	s_waitcnt vmcnt(8)
	s_waitcnt lgkmcnt(0)
	s_barrier
	s_setprio 1
	s_waitcnt lgkmcnt(0)
	v_mfma_f32_16x16x32_bf16 v[126:129], v[130:133], v[194:197], v[126:129]
	v_mfma_f32_16x16x32_bf16 v[122:125], v[138:141], v[194:197], v[122:125]
	v_mfma_f32_16x16x32_bf16 v[110:113], v[130:133], v[210:213], v[110:113]
	v_mfma_f32_16x16x32_bf16 v[106:109], v[138:141], v[210:213], v[106:109]
	v_mfma_f32_16x16x32_bf16 v[94:97], v[130:133], v[218:221], v[94:97]
	v_mfma_f32_16x16x32_bf16 v[90:93], v[138:141], v[218:221], v[90:93]
	v_mfma_f32_16x16x32_bf16 v[78:81], v[130:133], v[226:229], v[78:81]
	v_mfma_f32_16x16x32_bf16 v[74:77], v[138:141], v[226:229], v[74:77]
	v_mfma_f32_16x16x32_bf16 v[126:129], v[134:137], v[198:201], v[126:129]
	v_mfma_f32_16x16x32_bf16 v[122:125], v[142:145], v[198:201], v[122:125]
	v_mfma_f32_16x16x32_bf16 v[110:113], v[134:137], v[214:217], v[110:113]
	v_mfma_f32_16x16x32_bf16 v[106:109], v[142:145], v[214:217], v[106:109]
	v_mfma_f32_16x16x32_bf16 v[94:97], v[134:137], v[222:225], v[94:97]
	v_mfma_f32_16x16x32_bf16 v[90:93], v[142:145], v[222:225], v[90:93]
	v_mfma_f32_16x16x32_bf16 v[78:81], v[134:137], v[230:233], v[78:81]
	v_mfma_f32_16x16x32_bf16 v[74:77], v[142:145], v[230:233], v[74:77]
	v_mfma_f32_16x16x32_bf16 v[118:121], v[172:175], v[194:197], v[118:121]
	v_mfma_f32_16x16x32_bf16 v[114:117], v[186:189], v[194:197], v[114:117]
	v_mfma_f32_16x16x32_bf16 v[102:105], v[172:175], v[210:213], v[102:105]
	v_mfma_f32_16x16x32_bf16 v[98:101], v[186:189], v[210:213], v[98:101]
	v_mfma_f32_16x16x32_bf16 v[86:89], v[172:175], v[218:221], v[86:89]
	v_mfma_f32_16x16x32_bf16 v[82:85], v[186:189], v[218:221], v[82:85]
	v_mfma_f32_16x16x32_bf16 v[70:73], v[172:175], v[226:229], v[70:73]
	v_mfma_f32_16x16x32_bf16 v[66:69], v[186:189], v[226:229], v[66:69]
	v_mfma_f32_16x16x32_bf16 v[118:121], v[176:179], v[198:201], v[118:121]
	v_mfma_f32_16x16x32_bf16 v[114:117], v[190:193], v[198:201], v[114:117]
	v_mfma_f32_16x16x32_bf16 v[102:105], v[176:179], v[214:217], v[102:105]
	v_mfma_f32_16x16x32_bf16 v[98:101], v[190:193], v[214:217], v[98:101]
	v_mfma_f32_16x16x32_bf16 v[86:89], v[176:179], v[222:225], v[86:89]
	v_mfma_f32_16x16x32_bf16 v[82:85], v[190:193], v[222:225], v[82:85]
	v_mfma_f32_16x16x32_bf16 v[70:73], v[176:179], v[230:233], v[70:73]
	v_mfma_f32_16x16x32_bf16 v[66:69], v[190:193], v[230:233], v[66:69]
	s_setprio 0
	s_barrier
; #define PG8_STAGE(bufoff, gbase, voff) do { _Pragma("unroll") for (int _i = 0; _i < 2; ++_i) \
;         __builtin_amdgcn_global_load_lds((const unsigned*)((const char*)(gbase) + (voff)[_i]), (PG8_LAS unsigned*)(lds + (bufoff) + ldsw + _i * 8192), 16, 0, 0); } while (0)
; #define PG8_LDA(dst, b, h) do { _Pragma("unroll") for (int m = 0; m < 4; ++m) _Pragma("unroll") for (int k = 0; k < 2; ++k) dst[m][k] = *(const PG8_LAS bf16x8*)(lds + PG8_SA(b, h) + aoff + m * 2048 + k * 1024); } while (0)
; #define PG8_BAR __builtin_amdgcn_s_barrier()
; template <class Epi, class Sched, bool ALIGN_EPI = false, bool SP2 = false>
; __device__ __forceinline__ void gemm_phase(PG8_LAS unsigned char* lds, const Gemm g, const Sched& S, const Epi& E, const int wave_s) {
;     ...
;             PG8_LDA(At, 1, 1); PG8_STAGE(PG8_SB(1, 0), b3, voffB); PG8_STAGE(PG8_SB(1, 1), b3 + hstep, voffB); PG8_STAGE(PG8_SA(1, 0), a3, voffA);
;             PG8_WAIT_V(8); PG8_WAIT_L(0); PG8_BAR; PG8_MMA(1, 0, At, B0); PG8_MMA(1, 1, At, B1); PG8_BAR; PG8_SCHED;
;             } else {
;             PG8_LDB(B0, 0, 0); PG8_SCHED; PG8_LDA(At, 0, 0); PG8_STAGE(PG8_SA(1, 1), a1 + hstep, voffA);
;             PG8_WAIT_L(8); PG8_BAR; PG8_WAIT_L(0); PG8_MMA(0, 0, At, B0); PG8_BAR; PG8_SCHED;
;             PG8_LDB(B1, 0, 1); PG8_STAGE(PG8_SB(0, 0), b2, voffB);
;             PG8_BAR; PG8_WAIT_L(0); PG8_MMA(0, 1, At, B1); PG8_BAR;
;             PG8_LDA(At, 0, 1); PG8_STAGE(PG8_SA(0, 0), a2, voffA);
;             PG8_BAR; PG8_WAIT_L(0); PG8_MMA(1, 0, At, B0); PG8_BAR; PG8_SCHED;
;             PG8_STAGE(PG8_SB(0, 1), b2 + hstep, voffB);
;             PG8_WAIT_V(6); PG8_BAR; PG8_MMA(1, 1, At, B1); PG8_BAR;
;             PG8_LDB(B0, 1, 0); PG8_SCHED; PG8_LDA(At, 1, 0); PG8_STAGE(PG8_SA(0, 1), a2 + hstep, voffA);
;             PG8_WAIT_L(8); PG8_BAR; PG8_WAIT_L(0); PG8_MMA(0, 0, At, B0); PG8_BAR; PG8_SCHED;
;             PG8_LDB(B1, 1, 1); PG8_STAGE(PG8_SB(1, 0), b3, voffB);
;             PG8_BAR; PG8_WAIT_L(0); PG8_MMA(0, 1, At, B1); PG8_BAR;
;             PG8_LDA(At, 1, 1); PG8_STAGE(PG8_SA(1, 0), a3, voffA);
;             PG8_BAR; PG8_WAIT_L(0); PG8_MMA(1, 0, At, B0); PG8_BAR; PG8_SCHED;
;             PG8_STAGE(PG8_SB(1, 1), b3 + hstep, voffB);
;             PG8_WAIT_V(6); PG8_BAR; PG8_MMA(1, 1, At, B1); PG8_BAR;
;             }
;         }
;         if constexpr (ALIGN_EPI) { if (wr == 0) PG8_BAR; }
	s_add_i32 s34, s45, s44
	v_lshl_add_u64 v[202:203], v[202:203], 0, s[70:71]
	s_mov_b32 m0, s34
	ds_read_b128 v[194:197], v185 offset:49152
	ds_read_b128 v[198:201], v185 offset:50176
	ds_read_b128 v[210:213], v185 offset:51200
	ds_read_b128 v[214:217], v185 offset:52224
	ds_read_b128 v[218:221], v185 offset:53248
	ds_read_b128 v[222:225], v185 offset:54272
	ds_read_b128 v[226:229], v185 offset:55296
	ds_read_b128 v[230:233], v185 offset:56320
	global_load_lds_dwordx4 v[202:203], off
	s_add_i32 m0, s34, 0x2000
	s_add_u32 s30, s30, 0x40080
	v_lshl_add_u64 v[202:203], v[234:235], 0, s[70:71]
	s_addc_u32 s31, s31, 0
	s_add_i32 s34, s75, s44
	global_load_lds_dwordx4 v[202:203], off
	v_lshl_add_u64 v[202:203], s[30:31], 0, v[148:149]
	s_mov_b32 m0, s34
	s_nop 0
	global_load_lds_dwordx4 v[202:203], off
	v_lshl_add_u64 v[202:203], s[30:31], 0, v[152:153]
	s_add_i32 m0, s34, 0x2000
	s_nop 0
	global_load_lds_dwordx4 v[202:203], off
	v_lshl_add_u64 v[202:203], v[236:237], 0, s[70:71]
	s_mov_b32 m0, s88
	s_nop 0
	global_load_lds_dwordx4 v[202:203], off
	v_lshl_add_u64 v[202:203], v[238:239], 0, s[70:71]
	s_mov_b32 m0, s89
	s_nop 0
	global_load_lds_dwordx4 v[202:203], off
	s_waitcnt vmcnt(8)
	s_waitcnt lgkmcnt(0)
	s_barrier
	s_setprio 1
	s_waitcnt lgkmcnt(0)
	v_mfma_f32_16x16x32_bf16 v[62:65], v[130:133], v[194:197], v[62:65]
	v_mfma_f32_16x16x32_bf16 v[58:61], v[138:141], v[194:197], v[58:61]
	v_mfma_f32_16x16x32_bf16 v[46:49], v[130:133], v[210:213], v[46:49]
	v_mfma_f32_16x16x32_bf16 v[42:45], v[138:141], v[210:213], v[42:45]
	v_mfma_f32_16x16x32_bf16 v[30:33], v[130:133], v[218:221], v[30:33]
	v_mfma_f32_16x16x32_bf16 v[26:29], v[138:141], v[218:221], v[26:29]
	v_mfma_f32_16x16x32_bf16 v[14:17], v[130:133], v[226:229], v[14:17]
	v_mfma_f32_16x16x32_bf16 v[10:13], v[138:141], v[226:229], v[10:13]
	v_mfma_f32_16x16x32_bf16 v[62:65], v[134:137], v[198:201], v[62:65]
	v_mfma_f32_16x16x32_bf16 v[58:61], v[142:145], v[198:201], v[58:61]
	v_mfma_f32_16x16x32_bf16 v[46:49], v[134:137], v[214:217], v[46:49]
	v_mfma_f32_16x16x32_bf16 v[42:45], v[142:145], v[214:217], v[42:45]
	v_mfma_f32_16x16x32_bf16 v[30:33], v[134:137], v[222:225], v[30:33]
	v_mfma_f32_16x16x32_bf16 v[26:29], v[142:145], v[222:225], v[26:29]
	v_mfma_f32_16x16x32_bf16 v[14:17], v[134:137], v[230:233], v[14:17]
	v_mfma_f32_16x16x32_bf16 v[10:13], v[142:145], v[230:233], v[10:13]
	v_mfma_f32_16x16x32_bf16 v[54:57], v[172:175], v[194:197], v[54:57]
	v_mfma_f32_16x16x32_bf16 v[50:53], v[186:189], v[194:197], v[50:53]
	v_mfma_f32_16x16x32_bf16 v[38:41], v[172:175], v[210:213], v[38:41]
	v_mfma_f32_16x16x32_bf16 v[34:37], v[186:189], v[210:213], v[34:37]
	v_mfma_f32_16x16x32_bf16 v[22:25], v[172:175], v[218:221], v[22:25]
	v_mfma_f32_16x16x32_bf16 v[18:21], v[186:189], v[218:221], v[18:21]
	v_mfma_f32_16x16x32_bf16 v[6:9], v[172:175], v[226:229], v[6:9]
	v_mfma_f32_16x16x32_bf16 v[2:5], v[186:189], v[226:229], v[2:5]
	v_mfma_f32_16x16x32_bf16 v[54:57], v[176:179], v[198:201], v[54:57]
	v_mfma_f32_16x16x32_bf16 v[50:53], v[190:193], v[198:201], v[50:53]
	v_mfma_f32_16x16x32_bf16 v[38:41], v[176:179], v[214:217], v[38:41]
	v_mfma_f32_16x16x32_bf16 v[34:37], v[190:193], v[214:217], v[34:37]
	v_mfma_f32_16x16x32_bf16 v[22:25], v[176:179], v[222:225], v[22:25]
	v_mfma_f32_16x16x32_bf16 v[18:21], v[190:193], v[222:225], v[18:21]
	v_mfma_f32_16x16x32_bf16 v[6:9], v[176:179], v[230:233], v[6:9]
	v_mfma_f32_16x16x32_bf16 v[2:5], v[190:193], v[230:233], v[2:5]
	s_setprio 0
	s_barrier
	s_add_i32 s68, s68, 2
	s_add_u32 s28, s28, 0x100
	s_addc_u32 s29, s29, 0
	s_add_u32 s64, s64, 0x100
	s_addc_u32 s65, s65, 0
	s_cmp_gt_u32 s68, 13
	s_cbranch_scc0 .LBB0_325
	s_and_b64 vcc, exec, s[14:15]
	s_cbranch_vccz .LBB0_328
	s_barrier

; #define PG8_STAGE(bufoff, gbase, voff) do { _Pragma("unroll") for (int _i = 0; _i < 2; ++_i) \
;         __builtin_amdgcn_global_load_lds((const unsigned*)((const char*)(gbase) + (voff)[_i]), (PG8_LAS unsigned*)(lds + (bufoff) + ldsw + _i * 8192), 16, 0, 0); } while (0)
; #define PG8_LDA(dst, b, h) do { _Pragma("unroll") for (int m = 0; m < 4; ++m) _Pragma("unroll") for (int k = 0; k < 2; ++k) dst[m][k] = *(const PG8_LAS bf16x8*)(lds + PG8_SA(b, h) + aoff + m * 2048 + k * 1024); } while (0)
; #define PG8_LDB(dst, b, h) do { _Pragma("unroll") for (int n = 0; n < 2; ++n) _Pragma("unroll") for (int k = 0; k < 2; ++k) dst[n][k] = *(const PG8_LAS bf16x8*)(lds + PG8_SB(b, h) + boff + n * 2048 + k * 1024); } while (0)
; #define PG8_MMA(ai, bj, At, Bt) do { __builtin_amdgcn_s_setprio(1); _Pragma("unroll") for (int m = 0; m < 4; ++m) _Pragma("unroll") for (int n = 0; n < 2; ++n) _Pragma("unroll") for (int k = 0; k < 2; ++k) \
;         acc[ai][bj][m][n] = __builtin_amdgcn_mfma_f32_16x16x32_bf16(Bt[n][k], At[m][k], acc[ai][bj][m][n], 0, 0, 0); __builtin_amdgcn_s_setprio(0); } while (0)
; #define PG8_WAIT_V(n) asm volatile("s_waitcnt vmcnt(" #n ")" ::: "memory")
; #define PG8_WAIT_L(n) asm volatile("s_waitcnt lgkmcnt(" #n ")" ::: "memory")
; template <class Epi, class Sched, bool ALIGN_EPI = false, bool SP2 = false>
; __device__ __forceinline__ void gemm_phase(PG8_LAS unsigned char* lds, const Gemm g, const Sched& S, const Epi& E, const int wave_s) {
;     ...
;             const bool last = (t == nt - 2);
;             const char* a1 = cA + (size_t)(t + 1) * kstep;
;             const char* a2 = last ? nA : cA + (size_t)(t + 2) * kstep; const char* b2 = last ? nB : cB + (size_t)(t + 2) * kstep;
;             const char* a3 = a2 + kstep; const char* b3 = b2 + kstep;
;             if (last && has_next) S.a_ready(nxt);
;             if constexpr (SP2) {
;             PG8_LDB(B0, 0, 0); PG8_LDB(B1, 0, 1); PG8_SCHED; PG8_LDA(At, 0, 0); PG8_STAGE(PG8_SA(1, 1), a1 + hstep, voffA);
;             PG8_WAIT_V(8); PG8_WAIT_L(0); PG8_BAR; PG8_MMA(0, 0, At, B0); PG8_MMA(0, 1, At, B1); PG8_BAR; PG8_SCHED;
;             PG8_LDA(At, 0, 1); PG8_STAGE(PG8_SB(0, 0), b2, voffB); PG8_STAGE(PG8_SB(0, 1), b2 + hstep, voffB); PG8_STAGE(PG8_SA(0, 0), a2, voffA);
;             PG8_WAIT_V(8); PG8_WAIT_L(0); PG8_BAR; PG8_MMA(1, 0, At, B0); PG8_MMA(1, 1, At, B1); PG8_BAR; PG8_SCHED;
.LBB0_658:
	s_add_u32 s36, s34, 0xfffc0080
	s_addc_u32 s37, s35, -1
	s_add_i32 s45, 0, 0x10000
	s_cmp_eq_u32 s50, 12
	s_cselect_b32 s41, s27, s37
	s_cselect_b32 s40, s55, s36
	v_add_u32_e32 v152, s45, v195
	s_cselect_b32 s37, s25, vcc_hi
	s_cselect_b32 s36, s97, vcc_lo
	s_add_i32 s75, 0, 0x14000
	ds_read_b128 v[94:97], v152
	ds_read_b128 v[98:101], v152 offset:1024
	ds_read_b128 v[148:151], v152 offset:2048
	ds_read_b128 v[162:165], v152 offset:3072
	v_add_u32_e32 v152, s75, v195
	ds_read_b128 v[166:169], v152
	ds_read_b128 v[170:173], v152 offset:1024
	ds_read_b128 v[174:177], v152 offset:2048
	ds_read_b128 v[178:181], v152 offset:3072
	v_lshl_add_u64 v[152:153], s[34:35], 0, v[144:145]
	s_add_i32 m0, s88, 0xc000
	ds_read_b128 v[182:185], v198
	ds_read_b128 v[186:189], v198 offset:1024
	ds_read_b128 v[190:193], v198 offset:2048
	ds_read_b128 v[200:203], v198 offset:3072
	ds_read_b128 v[210:213], v198 offset:4096
	ds_read_b128 v[214:217], v198 offset:5120
	ds_read_b128 v[218:221], v198 offset:6144
	ds_read_b128 v[222:225], v198 offset:7168
	global_load_lds_dwordx4 v[152:153], off
	v_lshl_add_u64 v[152:153], s[34:35], 0, v[146:147]
	s_add_i32 m0, s88, 0xe000
	s_nop 0
	global_load_lds_dwordx4 v[152:153], off
	s_waitcnt vmcnt(8)
	s_waitcnt lgkmcnt(0)
	s_barrier
	s_setprio 1
	s_waitcnt lgkmcnt(0)
	v_mfma_f32_16x16x32_bf16 v[134:137], v[94:97], v[182:185], v[134:137]
	v_mfma_f32_16x16x32_bf16 v[130:133], v[148:151], v[182:185], v[130:133]
	v_mfma_f32_16x16x32_bf16 v[126:129], v[94:97], v[190:193], v[126:129]
	v_mfma_f32_16x16x32_bf16 v[122:125], v[148:151], v[190:193], v[122:125]
	v_mfma_f32_16x16x32_bf16 v[118:121], v[94:97], v[210:213], v[118:121]
	v_mfma_f32_16x16x32_bf16 v[114:117], v[148:151], v[210:213], v[114:117]
	v_mfma_f32_16x16x32_bf16 v[110:113], v[94:97], v[218:221], v[110:113]
	v_mfma_f32_16x16x32_bf16 v[106:109], v[148:151], v[218:221], v[106:109]
	v_mfma_f32_16x16x32_bf16 v[134:137], v[98:101], v[186:189], v[134:137]
	v_mfma_f32_16x16x32_bf16 v[130:133], v[162:165], v[186:189], v[130:133]
	v_mfma_f32_16x16x32_bf16 v[126:129], v[98:101], v[200:203], v[126:129]
	v_mfma_f32_16x16x32_bf16 v[122:125], v[162:165], v[200:203], v[122:125]
	v_mfma_f32_16x16x32_bf16 v[118:121], v[98:101], v[214:217], v[118:121]
	v_mfma_f32_16x16x32_bf16 v[114:117], v[162:165], v[214:217], v[114:117]
	v_mfma_f32_16x16x32_bf16 v[110:113], v[98:101], v[222:225], v[110:113]
	v_mfma_f32_16x16x32_bf16 v[106:109], v[162:165], v[222:225], v[106:109]
	v_mfma_f32_16x16x32_bf16 v[58:61], v[166:169], v[182:185], v[58:61]
	v_mfma_f32_16x16x32_bf16 v[62:65], v[174:177], v[182:185], v[62:65]
	v_mfma_f32_16x16x32_bf16 v[54:57], v[166:169], v[190:193], v[54:57]
	v_mfma_f32_16x16x32_bf16 v[50:53], v[174:177], v[190:193], v[50:53]
	v_mfma_f32_16x16x32_bf16 v[46:49], v[166:169], v[210:213], v[46:49]
	v_mfma_f32_16x16x32_bf16 v[42:45], v[174:177], v[210:213], v[42:45]
	v_mfma_f32_16x16x32_bf16 v[38:41], v[166:169], v[218:221], v[38:41]
	v_mfma_f32_16x16x32_bf16 v[34:37], v[174:177], v[218:221], v[34:37]
	v_mfma_f32_16x16x32_bf16 v[58:61], v[170:173], v[186:189], v[58:61]
	v_mfma_f32_16x16x32_bf16 v[62:65], v[178:181], v[186:189], v[62:65]
	v_mfma_f32_16x16x32_bf16 v[54:57], v[170:173], v[200:203], v[54:57]
	v_mfma_f32_16x16x32_bf16 v[50:53], v[178:181], v[200:203], v[50:53]
	v_mfma_f32_16x16x32_bf16 v[46:49], v[170:173], v[214:217], v[46:49]
	v_mfma_f32_16x16x32_bf16 v[42:45], v[178:181], v[214:217], v[42:45]
	v_mfma_f32_16x16x32_bf16 v[38:41], v[170:173], v[222:225], v[38:41]
	v_mfma_f32_16x16x32_bf16 v[34:37], v[178:181], v[222:225], v[34:37]
	s_setprio 0
	s_barrier
	s_add_i32 s45, s45, s68
	v_lshl_add_u64 v[152:153], s[36:37], 0, v[0:1]
	s_mov_b32 m0, s45
	ds_read_b128 v[182:185], v198 offset:16384
	ds_read_b128 v[186:189], v198 offset:17408
	ds_read_b128 v[190:193], v198 offset:18432
	ds_read_b128 v[200:203], v198 offset:19456
	ds_read_b128 v[210:213], v198 offset:20480
	ds_read_b128 v[214:217], v198 offset:21504
	ds_read_b128 v[218:221], v198 offset:22528
	ds_read_b128 v[222:225], v198 offset:23552
	global_load_lds_dwordx4 v[152:153], off
	s_add_i32 m0, s45, 0x2000
	s_add_u32 s80, s36, 0x40000
	v_lshl_add_u64 v[226:227], s[36:37], 0, v[138:139]
	s_addc_u32 s81, s37, 0
	s_add_i32 s45, s75, s68
	global_load_lds_dwordx4 v[226:227], off
	v_lshl_add_u64 v[228:229], s[80:81], 0, v[0:1]
	s_mov_b32 m0, s45
	v_lshl_add_u64 v[230:231], s[40:41], 0, v[140:141]
	global_load_lds_dwordx4 v[228:229], off
	v_lshl_add_u64 v[228:229], s[80:81], 0, v[138:139]
	s_add_i32 m0, s45, 0x2000
	s_nop 0
	global_load_lds_dwordx4 v[228:229], off
	v_lshl_add_u64 v[228:229], s[40:41], 0, v[142:143]
	s_mov_b32 m0, s88
	s_nop 0
	global_load_lds_dwordx4 v[228:229], off
	s_mov_b32 m0, s89
	s_nop 0
	global_load_lds_dwordx4 v[230:231], off
	s_waitcnt vmcnt(8)
	s_waitcnt lgkmcnt(0)
	s_barrier
; #define PG8_STAGE(bufoff, gbase, voff) do { _Pragma("unroll") for (int _i = 0; _i < 2; ++_i) \
;         __builtin_amdgcn_global_load_lds((const unsigned*)((const char*)(gbase) + (voff)[_i]), (PG8_LAS unsigned*)(lds + (bufoff) + ldsw + _i * 8192), 16, 0, 0); } while (0)
; #define PG8_LDA(dst, b, h) do { _Pragma("unroll") for (int m = 0; m < 4; ++m) _Pragma("unroll") for (int k = 0; k < 2; ++k) dst[m][k] = *(const PG8_LAS bf16x8*)(lds + PG8_SA(b, h) + aoff + m * 2048 + k * 1024); } while (0)
; #define PG8_LDB(dst, b, h) do { _Pragma("unroll") for (int n = 0; n < 2; ++n) _Pragma("unroll") for (int k = 0; k < 2; ++k) dst[n][k] = *(const PG8_LAS bf16x8*)(lds + PG8_SB(b, h) + boff + n * 2048 + k * 1024); } while (0)
; #define PG8_MMA(ai, bj, At, Bt) do { __builtin_amdgcn_s_setprio(1); _Pragma("unroll") for (int m = 0; m < 4; ++m) _Pragma("unroll") for (int n = 0; n < 2; ++n) _Pragma("unroll") for (int k = 0; k < 2; ++k) \
;         acc[ai][bj][m][n] = __builtin_amdgcn_mfma_f32_16x16x32_bf16(Bt[n][k], At[m][k], acc[ai][bj][m][n], 0, 0, 0); __builtin_amdgcn_s_setprio(0); } while (0)
; #define PG8_WAIT_V(n) asm volatile("s_waitcnt vmcnt(" #n ")" ::: "memory")
; #define PG8_WAIT_L(n) asm volatile("s_waitcnt lgkmcnt(" #n ")" ::: "memory")
; #define PG8_BAR __builtin_amdgcn_s_barrier()
; #define PG8_SCHED __builtin_amdgcn_sched_barrier(0)
; template <class Epi, class Sched, bool ALIGN_EPI = false, bool SP2 = false>
; __device__ __forceinline__ void gemm_phase(PG8_LAS unsigned char* lds, const Gemm g, const Sched& S, const Epi& E, const int wave_s) {
;     ...
;             PG8_WAIT_V(8); PG8_WAIT_L(0); PG8_BAR; PG8_MMA(1, 0, At, B0); PG8_MMA(1, 1, At, B1); PG8_BAR; PG8_SCHED;
;             PG8_LDB(B0, 1, 0); PG8_LDB(B1, 1, 1); PG8_SCHED; PG8_LDA(At, 1, 0); PG8_STAGE(PG8_SA(0, 1), a2 + hstep, voffA);
;             PG8_WAIT_V(8); PG8_WAIT_L(0); PG8_BAR; PG8_MMA(0, 0, At, B0); PG8_MMA(0, 1, At, B1); PG8_BAR; PG8_SCHED;
	s_setprio 1
	s_waitcnt lgkmcnt(0)
	v_mfma_f32_16x16x32_bf16 v[102:105], v[94:97], v[182:185], v[102:105]
	v_mfma_f32_16x16x32_bf16 v[90:93], v[148:151], v[182:185], v[90:93]
	v_mfma_f32_16x16x32_bf16 v[86:89], v[94:97], v[190:193], v[86:89]
	v_mfma_f32_16x16x32_bf16 v[82:85], v[148:151], v[190:193], v[82:85]
	v_mfma_f32_16x16x32_bf16 v[78:81], v[94:97], v[210:213], v[78:81]
	v_mfma_f32_16x16x32_bf16 v[74:77], v[148:151], v[210:213], v[74:77]
	v_mfma_f32_16x16x32_bf16 v[70:73], v[94:97], v[218:221], v[70:73]
	v_mfma_f32_16x16x32_bf16 v[66:69], v[148:151], v[218:221], v[66:69]
	v_mfma_f32_16x16x32_bf16 v[102:105], v[98:101], v[186:189], v[102:105]
	v_mfma_f32_16x16x32_bf16 v[90:93], v[162:165], v[186:189], v[90:93]
	v_mfma_f32_16x16x32_bf16 v[86:89], v[98:101], v[200:203], v[86:89]
	v_mfma_f32_16x16x32_bf16 v[82:85], v[162:165], v[200:203], v[82:85]
	v_mfma_f32_16x16x32_bf16 v[78:81], v[98:101], v[214:217], v[78:81]
	v_mfma_f32_16x16x32_bf16 v[74:77], v[162:165], v[214:217], v[74:77]
	v_mfma_f32_16x16x32_bf16 v[70:73], v[98:101], v[222:225], v[70:73]
	v_mfma_f32_16x16x32_bf16 v[66:69], v[162:165], v[222:225], v[66:69]
	v_mfma_f32_16x16x32_bf16 v[30:33], v[166:169], v[182:185], v[30:33]
	v_mfma_f32_16x16x32_bf16 v[26:29], v[174:177], v[182:185], v[26:29]
	v_mfma_f32_16x16x32_bf16 v[22:25], v[166:169], v[190:193], v[22:25]
	v_mfma_f32_16x16x32_bf16 v[18:21], v[174:177], v[190:193], v[18:21]
	v_mfma_f32_16x16x32_bf16 v[14:17], v[166:169], v[210:213], v[14:17]
	v_mfma_f32_16x16x32_bf16 v[10:13], v[174:177], v[210:213], v[10:13]
	v_mfma_f32_16x16x32_bf16 v[6:9], v[166:169], v[218:221], v[6:9]
	v_mfma_f32_16x16x32_bf16 v[2:5], v[174:177], v[218:221], v[2:5]
	v_mfma_f32_16x16x32_bf16 v[30:33], v[170:173], v[186:189], v[30:33]
	v_mfma_f32_16x16x32_bf16 v[26:29], v[178:181], v[186:189], v[26:29]
	v_mfma_f32_16x16x32_bf16 v[22:25], v[170:173], v[200:203], v[22:25]
	v_mfma_f32_16x16x32_bf16 v[18:21], v[178:181], v[200:203], v[18:21]
	v_mfma_f32_16x16x32_bf16 v[14:17], v[170:173], v[214:217], v[14:17]
	v_mfma_f32_16x16x32_bf16 v[10:13], v[178:181], v[214:217], v[10:13]
	v_mfma_f32_16x16x32_bf16 v[6:9], v[170:173], v[222:225], v[6:9]
	v_mfma_f32_16x16x32_bf16 v[2:5], v[178:181], v[222:225], v[2:5]
	s_setprio 0
	s_barrier
	s_add_i32 s45, 0, 0x18000
	s_add_i32 s75, 0, 0x1c000
	v_add_u32_e32 v162, s45, v195
	v_add_u32_e32 v178, s75, v195
	ds_read_b128 v[94:97], v162
	ds_read_b128 v[98:101], v162 offset:1024
	ds_read_b128 v[148:151], v162 offset:2048
	ds_read_b128 v[162:165], v162 offset:3072
	ds_read_b128 v[166:169], v178
	ds_read_b128 v[170:173], v178 offset:1024
	ds_read_b128 v[174:177], v178 offset:2048
	ds_read_b128 v[178:181], v178 offset:3072
	s_add_u32 s40, s40, 0x40000
	s_addc_u32 s41, s41, 0
	s_mov_b32 m0, s38
	v_lshl_add_u64 v[232:233], s[40:41], 0, v[142:143]
	ds_read_b128 v[182:185], v198 offset:32768
	ds_read_b128 v[186:189], v198 offset:33792
	ds_read_b128 v[190:193], v198 offset:34816
	ds_read_b128 v[200:203], v198 offset:35840
	ds_read_b128 v[210:213], v198 offset:36864
	ds_read_b128 v[214:217], v198 offset:37888
	ds_read_b128 v[218:221], v198 offset:38912
	ds_read_b128 v[222:225], v198 offset:39936
	global_load_lds_dwordx4 v[232:233], off
	v_lshl_add_u64 v[232:233], s[40:41], 0, v[140:141]
	s_mov_b32 m0, s39
	s_nop 0
	global_load_lds_dwordx4 v[232:233], off
	s_waitcnt vmcnt(8)
	s_waitcnt lgkmcnt(0)
	s_barrier
	s_setprio 1
	s_waitcnt lgkmcnt(0)
	v_mfma_f32_16x16x32_bf16 v[134:137], v[94:97], v[182:185], v[134:137]
	v_mfma_f32_16x16x32_bf16 v[130:133], v[148:151], v[182:185], v[130:133]
	v_mfma_f32_16x16x32_bf16 v[126:129], v[94:97], v[190:193], v[126:129]
	v_mfma_f32_16x16x32_bf16 v[122:125], v[148:151], v[190:193], v[122:125]
	v_mfma_f32_16x16x32_bf16 v[118:121], v[94:97], v[210:213], v[118:121]
	v_mfma_f32_16x16x32_bf16 v[114:117], v[148:151], v[210:213], v[114:117]
	v_mfma_f32_16x16x32_bf16 v[110:113], v[94:97], v[218:221], v[110:113]
	v_mfma_f32_16x16x32_bf16 v[106:109], v[148:151], v[218:221], v[106:109]
	v_mfma_f32_16x16x32_bf16 v[134:137], v[98:101], v[186:189], v[134:137]
	v_mfma_f32_16x16x32_bf16 v[130:133], v[162:165], v[186:189], v[130:133]
	v_mfma_f32_16x16x32_bf16 v[126:129], v[98:101], v[200:203], v[126:129]
	v_mfma_f32_16x16x32_bf16 v[122:125], v[162:165], v[200:203], v[122:125]
	v_mfma_f32_16x16x32_bf16 v[118:121], v[98:101], v[214:217], v[118:121]
	v_mfma_f32_16x16x32_bf16 v[114:117], v[162:165], v[214:217], v[114:117]
	v_mfma_f32_16x16x32_bf16 v[110:113], v[98:101], v[222:225], v[110:113]
	v_mfma_f32_16x16x32_bf16 v[106:109], v[162:165], v[222:225], v[106:109]
	v_mfma_f32_16x16x32_bf16 v[58:61], v[166:169], v[182:185], v[58:61]
	v_mfma_f32_16x16x32_bf16 v[62:65], v[174:177], v[182:185], v[62:65]
	v_mfma_f32_16x16x32_bf16 v[54:57], v[166:169], v[190:193], v[54:57]
	v_mfma_f32_16x16x32_bf16 v[50:53], v[174:177], v[190:193], v[50:53]
	v_mfma_f32_16x16x32_bf16 v[46:49], v[166:169], v[210:213], v[46:49]
	v_mfma_f32_16x16x32_bf16 v[42:45], v[174:177], v[210:213], v[42:45]
	v_mfma_f32_16x16x32_bf16 v[38:41], v[166:169], v[218:221], v[38:41]
	v_mfma_f32_16x16x32_bf16 v[34:37], v[174:177], v[218:221], v[34:37]
	v_mfma_f32_16x16x32_bf16 v[58:61], v[170:173], v[186:189], v[58:61]
	v_mfma_f32_16x16x32_bf16 v[62:65], v[178:181], v[186:189], v[62:65]
	v_mfma_f32_16x16x32_bf16 v[54:57], v[170:173], v[200:203], v[54:57]
	v_mfma_f32_16x16x32_bf16 v[50:53], v[178:181], v[200:203], v[50:53]
	v_mfma_f32_16x16x32_bf16 v[46:49], v[170:173], v[214:217], v[46:49]
	v_mfma_f32_16x16x32_bf16 v[42:45], v[178:181], v[214:217], v[42:45]
	v_mfma_f32_16x16x32_bf16 v[38:41], v[170:173], v[222:225], v[38:41]
	v_mfma_f32_16x16x32_bf16 v[34:37], v[178:181], v[222:225], v[34:37]
	s_setprio 0
	s_barrier
; #define PG8_STAGE(bufoff, gbase, voff) do { _Pragma("unroll") for (int _i = 0; _i < 2; ++_i) \
;         __builtin_amdgcn_global_load_lds((const unsigned*)((const char*)(gbase) + (voff)[_i]), (PG8_LAS unsigned*)(lds + (bufoff) + ldsw + _i * 8192), 16, 0, 0); } while (0)
; #define PG8_LDA(dst, b, h) do { _Pragma("unroll") for (int m = 0; m < 4; ++m) _Pragma("unroll") for (int k = 0; k < 2; ++k) dst[m][k] = *(const PG8_LAS bf16x8*)(lds + PG8_SA(b, h) + aoff + m * 2048 + k * 1024); } while (0)
; #define PG8_BAR __builtin_amdgcn_s_barrier()
; template <class Epi, class Sched, bool ALIGN_EPI = false, bool SP2 = false>
; __device__ __forceinline__ void gemm_phase(PG8_LAS unsigned char* lds, const Gemm g, const Sched& S, const Epi& E, const int wave_s) {
;     ...
;             PG8_LDA(At, 1, 1); PG8_STAGE(PG8_SB(1, 0), b3, voffB); PG8_STAGE(PG8_SB(1, 1), b3 + hstep, voffB); PG8_STAGE(PG8_SA(1, 0), a3, voffA);
;             PG8_WAIT_V(8); PG8_WAIT_L(0); PG8_BAR; PG8_MMA(1, 0, At, B0); PG8_MMA(1, 1, At, B1); PG8_BAR; PG8_SCHED;
;             } else {
;             PG8_LDB(B0, 0, 0); PG8_SCHED; PG8_LDA(At, 0, 0); PG8_STAGE(PG8_SA(1, 1), a1 + hstep, voffA);
;             PG8_WAIT_L(8); PG8_BAR; PG8_WAIT_L(0); PG8_MMA(0, 0, At, B0); PG8_BAR; PG8_SCHED;
;             PG8_LDB(B1, 0, 1); PG8_STAGE(PG8_SB(0, 0), b2, voffB);
;             PG8_BAR; PG8_WAIT_L(0); PG8_MMA(0, 1, At, B1); PG8_BAR;
;             PG8_LDA(At, 0, 1); PG8_STAGE(PG8_SA(0, 0), a2, voffA);
;             PG8_BAR; PG8_WAIT_L(0); PG8_MMA(1, 0, At, B0); PG8_BAR; PG8_SCHED;
;             PG8_STAGE(PG8_SB(0, 1), b2 + hstep, voffB);
;             PG8_WAIT_V(6); PG8_BAR; PG8_MMA(1, 1, At, B1); PG8_BAR;
;             PG8_LDB(B0, 1, 0); PG8_SCHED; PG8_LDA(At, 1, 0); PG8_STAGE(PG8_SA(0, 1), a2 + hstep, voffA);
;             PG8_WAIT_L(8); PG8_BAR; PG8_WAIT_L(0); PG8_MMA(0, 0, At, B0); PG8_BAR; PG8_SCHED;
;             PG8_LDB(B1, 1, 1); PG8_STAGE(PG8_SB(1, 0), b3, voffB);
;             PG8_BAR; PG8_WAIT_L(0); PG8_MMA(0, 1, At, B1); PG8_BAR;
;             PG8_LDA(At, 1, 1); PG8_STAGE(PG8_SA(1, 0), a3, voffA);
;             PG8_BAR; PG8_WAIT_L(0); PG8_MMA(1, 0, At, B0); PG8_BAR; PG8_SCHED;
;             PG8_STAGE(PG8_SB(1, 1), b3 + hstep, voffB);
;             PG8_WAIT_V(6); PG8_BAR; PG8_MMA(1, 1, At, B1); PG8_BAR;
;             }
;         }
;         if constexpr (ALIGN_EPI) { if (wr == 0) PG8_BAR; }
	s_add_i32 s40, s45, s68
	v_lshl_add_u64 v[152:153], v[152:153], 0, s[70:71]
	s_mov_b32 m0, s40
	ds_read_b128 v[182:185], v198 offset:49152
	ds_read_b128 v[186:189], v198 offset:50176
	ds_read_b128 v[190:193], v198 offset:51200
	ds_read_b128 v[200:203], v198 offset:52224
	ds_read_b128 v[210:213], v198 offset:53248
	ds_read_b128 v[214:217], v198 offset:54272
	ds_read_b128 v[218:221], v198 offset:55296
	ds_read_b128 v[222:225], v198 offset:56320
	global_load_lds_dwordx4 v[152:153], off
	s_add_i32 m0, s40, 0x2000
	s_add_u32 s36, s36, 0x40080
	v_lshl_add_u64 v[152:153], v[226:227], 0, s[70:71]
	s_addc_u32 s37, s37, 0
	s_add_i32 s40, s75, s68
	global_load_lds_dwordx4 v[152:153], off
	v_lshl_add_u64 v[152:153], s[36:37], 0, v[0:1]
	s_mov_b32 m0, s40
	s_nop 0
	global_load_lds_dwordx4 v[152:153], off
	v_lshl_add_u64 v[152:153], s[36:37], 0, v[138:139]
	s_add_i32 m0, s40, 0x2000
	s_nop 0
	global_load_lds_dwordx4 v[152:153], off
	v_lshl_add_u64 v[152:153], v[228:229], 0, s[70:71]
	s_mov_b32 m0, s44
	s_nop 0
	global_load_lds_dwordx4 v[152:153], off
	v_lshl_add_u64 v[152:153], v[230:231], 0, s[70:71]
	s_mov_b32 m0, s54
	s_nop 0
	global_load_lds_dwordx4 v[152:153], off
	s_waitcnt vmcnt(8)
	s_waitcnt lgkmcnt(0)
	s_barrier
	s_setprio 1
	s_waitcnt lgkmcnt(0)
	v_mfma_f32_16x16x32_bf16 v[102:105], v[94:97], v[182:185], v[102:105]
	v_mfma_f32_16x16x32_bf16 v[90:93], v[148:151], v[182:185], v[90:93]
	v_mfma_f32_16x16x32_bf16 v[86:89], v[94:97], v[190:193], v[86:89]
	v_mfma_f32_16x16x32_bf16 v[82:85], v[148:151], v[190:193], v[82:85]
	v_mfma_f32_16x16x32_bf16 v[78:81], v[94:97], v[210:213], v[78:81]
	v_mfma_f32_16x16x32_bf16 v[74:77], v[148:151], v[210:213], v[74:77]
	v_mfma_f32_16x16x32_bf16 v[70:73], v[94:97], v[218:221], v[70:73]
	v_mfma_f32_16x16x32_bf16 v[66:69], v[148:151], v[218:221], v[66:69]
	v_mfma_f32_16x16x32_bf16 v[102:105], v[98:101], v[186:189], v[102:105]
	v_mfma_f32_16x16x32_bf16 v[90:93], v[162:165], v[186:189], v[90:93]
	v_mfma_f32_16x16x32_bf16 v[86:89], v[98:101], v[200:203], v[86:89]
	v_mfma_f32_16x16x32_bf16 v[82:85], v[162:165], v[200:203], v[82:85]
	v_mfma_f32_16x16x32_bf16 v[78:81], v[98:101], v[214:217], v[78:81]
	v_mfma_f32_16x16x32_bf16 v[74:77], v[162:165], v[214:217], v[74:77]
	v_mfma_f32_16x16x32_bf16 v[70:73], v[98:101], v[222:225], v[70:73]
	v_mfma_f32_16x16x32_bf16 v[66:69], v[162:165], v[222:225], v[66:69]
	v_mfma_f32_16x16x32_bf16 v[30:33], v[166:169], v[182:185], v[30:33]
	v_mfma_f32_16x16x32_bf16 v[26:29], v[174:177], v[182:185], v[26:29]
	v_mfma_f32_16x16x32_bf16 v[22:25], v[166:169], v[190:193], v[22:25]
	v_mfma_f32_16x16x32_bf16 v[18:21], v[174:177], v[190:193], v[18:21]
	v_mfma_f32_16x16x32_bf16 v[14:17], v[166:169], v[210:213], v[14:17]
	v_mfma_f32_16x16x32_bf16 v[10:13], v[174:177], v[210:213], v[10:13]
	v_mfma_f32_16x16x32_bf16 v[6:9], v[166:169], v[218:221], v[6:9]
	v_mfma_f32_16x16x32_bf16 v[2:5], v[174:177], v[218:221], v[2:5]
	v_mfma_f32_16x16x32_bf16 v[30:33], v[170:173], v[186:189], v[30:33]
	v_mfma_f32_16x16x32_bf16 v[26:29], v[178:181], v[186:189], v[26:29]
	v_mfma_f32_16x16x32_bf16 v[22:25], v[170:173], v[200:203], v[22:25]
	v_mfma_f32_16x16x32_bf16 v[18:21], v[178:181], v[200:203], v[18:21]
	v_mfma_f32_16x16x32_bf16 v[14:17], v[170:173], v[214:217], v[14:17]
	v_mfma_f32_16x16x32_bf16 v[10:13], v[178:181], v[214:217], v[10:13]
	v_mfma_f32_16x16x32_bf16 v[6:9], v[170:173], v[222:225], v[6:9]
	v_mfma_f32_16x16x32_bf16 v[2:5], v[178:181], v[222:225], v[2:5]
	s_setprio 0
	s_barrier
	s_add_i32 s50, s50, 2
	s_add_u32 s34, s34, 0x100
	s_addc_u32 s35, s35, 0
	s_add_u32 vcc_lo, vcc_lo, 0x100
	s_addc_u32 vcc_hi, vcc_hi, 0
	s_cmp_gt_u32 s50, 13
	s_cbranch_scc0 .LBB0_658
	s_and_b64 vcc, exec, s[22:23]
	s_cbranch_vccz .LBB0_661
	s_barrier

; #define PG8_STAGE(bufoff, gbase, voff) do { _Pragma("unroll") for (int _i = 0; _i < 2; ++_i) \
;         __builtin_amdgcn_global_load_lds((const unsigned*)((const char*)(gbase) + (voff)[_i]), (PG8_LAS unsigned*)(lds + (bufoff) + ldsw + _i * 8192), 16, 0, 0); } while (0)
; #define PG8_LDA(dst, b, h) do { _Pragma("unroll") for (int m = 0; m < 4; ++m) _Pragma("unroll") for (int k = 0; k < 2; ++k) dst[m][k] = *(const PG8_LAS bf16x8*)(lds + PG8_SA(b, h) + aoff + m * 2048 + k * 1024); } while (0)
; #define PG8_LDB(dst, b, h) do { _Pragma("unroll") for (int n = 0; n < 2; ++n) _Pragma("unroll") for (int k = 0; k < 2; ++k) dst[n][k] = *(const PG8_LAS bf16x8*)(lds + PG8_SB(b, h) + boff + n * 2048 + k * 1024); } while (0)
; #define PG8_MMA(ai, bj, At, Bt) do { __builtin_amdgcn_s_setprio(1); _Pragma("unroll") for (int m = 0; m < 4; ++m) _Pragma("unroll") for (int n = 0; n < 2; ++n) _Pragma("unroll") for (int k = 0; k < 2; ++k) \
;         acc[ai][bj][m][n] = __builtin_amdgcn_mfma_f32_16x16x32_bf16(Bt[n][k], At[m][k], acc[ai][bj][m][n], 0, 0, 0); __builtin_amdgcn_s_setprio(0); } while (0)
; #define PG8_WAIT_V(n) asm volatile("s_waitcnt vmcnt(" #n ")" ::: "memory")
; #define PG8_WAIT_L(n) asm volatile("s_waitcnt lgkmcnt(" #n ")" ::: "memory")
; template <class Epi, class Sched, bool ALIGN_EPI = false, bool SP2 = false>
; __device__ __forceinline__ void gemm_phase(PG8_LAS unsigned char* lds, const Gemm g, const Sched& S, const Epi& E, const int wave_s) {
;     ...
;             const bool last = (t == nt - 2);
;             const char* a1 = cA + (size_t)(t + 1) * kstep;
;             const char* a2 = last ? nA : cA + (size_t)(t + 2) * kstep; const char* b2 = last ? nB : cB + (size_t)(t + 2) * kstep;
;             const char* a3 = a2 + kstep; const char* b3 = b2 + kstep;
;             if (last && has_next) S.a_ready(nxt);
;             if constexpr (SP2) {
;             PG8_LDB(B0, 0, 0); PG8_LDB(B1, 0, 1); PG8_SCHED; PG8_LDA(At, 0, 0); PG8_STAGE(PG8_SA(1, 1), a1 + hstep, voffA);
;             PG8_WAIT_V(8); PG8_WAIT_L(0); PG8_BAR; PG8_MMA(0, 0, At, B0); PG8_MMA(0, 1, At, B1); PG8_BAR; PG8_SCHED;
;             PG8_LDA(At, 0, 1); PG8_STAGE(PG8_SB(0, 0), b2, voffB); PG8_STAGE(PG8_SB(0, 1), b2 + hstep, voffB); PG8_STAGE(PG8_SA(0, 0), a2, voffA);
;             PG8_WAIT_V(8); PG8_WAIT_L(0); PG8_BAR; PG8_MMA(1, 0, At, B0); PG8_MMA(1, 1, At, B1); PG8_BAR; PG8_SCHED;
.LBB0_734:
	s_add_u32 s26, s24, 0xfffc0080
	s_addc_u32 s27, s25, -1
	s_add_i32 s45, 0, 0x10000
	s_cmp_eq_u32 s50, 12
	s_cselect_b32 s29, s19, s27
	s_cselect_b32 s28, s54, s26
	s_cselect_b32 s27, s17, s59
	s_cselect_b32 s26, s55, s58
	s_add_i32 s68, 0, 0x14000
	v_add_u32_e32 v50, s45, v171
	v_add_u32_e32 v152, s68, v171
	ds_read_b128 v[26:29], v50
	ds_read_b128 v[30:33], v50 offset:1024
	ds_read_b128 v[46:49], v50 offset:2048
	ds_read_b128 v[50:53], v50 offset:3072
	ds_read_b128 v[162:165], v152
	ds_read_b128 v[166:169], v152 offset:1024
	ds_read_b128 v[176:179], v152 offset:2048
	ds_read_b128 v[180:183], v152 offset:3072
	v_lshl_add_u64 v[152:153], s[24:25], 0, v[148:149]
	s_add_i32 m0, s35, 0xc000
	ds_read_b128 v[184:187], v174
	ds_read_b128 v[188:191], v174 offset:1024
	ds_read_b128 v[192:195], v174 offset:2048
	ds_read_b128 v[196:199], v174 offset:3072
	ds_read_b128 v[200:203], v174 offset:4096
	ds_read_b128 v[210:213], v174 offset:5120
	ds_read_b128 v[214:217], v174 offset:6144
	ds_read_b128 v[218:221], v174 offset:7168
	global_load_lds_dwordx4 v[152:153], off
	v_lshl_add_u64 v[152:153], s[24:25], 0, v[150:151]
	s_add_i32 m0, s35, 0xe000
	s_nop 0
	global_load_lds_dwordx4 v[152:153], off
	s_waitcnt vmcnt(8)
	s_waitcnt lgkmcnt(0)
	s_barrier
	s_setprio 1
	s_waitcnt lgkmcnt(0)
	v_mfma_f32_16x16x32_bf16 v[142:145], v[26:29], v[184:187], v[142:145]
	v_mfma_f32_16x16x32_bf16 v[138:141], v[46:49], v[184:187], v[138:141]
	v_mfma_f32_16x16x32_bf16 v[126:129], v[26:29], v[192:195], v[126:129]
	v_mfma_f32_16x16x32_bf16 v[122:125], v[46:49], v[192:195], v[122:125]
	v_mfma_f32_16x16x32_bf16 v[110:113], v[26:29], v[200:203], v[110:113]
	v_mfma_f32_16x16x32_bf16 v[106:109], v[46:49], v[200:203], v[106:109]
	v_mfma_f32_16x16x32_bf16 v[94:97], v[26:29], v[214:217], v[94:97]
	v_mfma_f32_16x16x32_bf16 v[90:93], v[46:49], v[214:217], v[90:93]
	v_mfma_f32_16x16x32_bf16 v[142:145], v[30:33], v[188:191], v[142:145]
	v_mfma_f32_16x16x32_bf16 v[138:141], v[50:53], v[188:191], v[138:141]
	v_mfma_f32_16x16x32_bf16 v[126:129], v[30:33], v[196:199], v[126:129]
	v_mfma_f32_16x16x32_bf16 v[122:125], v[50:53], v[196:199], v[122:125]
	v_mfma_f32_16x16x32_bf16 v[110:113], v[30:33], v[210:213], v[110:113]
	v_mfma_f32_16x16x32_bf16 v[106:109], v[50:53], v[210:213], v[106:109]
	v_mfma_f32_16x16x32_bf16 v[94:97], v[30:33], v[218:221], v[94:97]
	v_mfma_f32_16x16x32_bf16 v[90:93], v[50:53], v[218:221], v[90:93]
	v_mfma_f32_16x16x32_bf16 v[134:137], v[162:165], v[184:187], v[134:137]
	v_mfma_f32_16x16x32_bf16 v[130:133], v[176:179], v[184:187], v[130:133]
	v_mfma_f32_16x16x32_bf16 v[118:121], v[162:165], v[192:195], v[118:121]
	v_mfma_f32_16x16x32_bf16 v[114:117], v[176:179], v[192:195], v[114:117]
	v_mfma_f32_16x16x32_bf16 v[102:105], v[162:165], v[200:203], v[102:105]
	v_mfma_f32_16x16x32_bf16 v[98:101], v[176:179], v[200:203], v[98:101]
	v_mfma_f32_16x16x32_bf16 v[86:89], v[162:165], v[214:217], v[86:89]
	v_mfma_f32_16x16x32_bf16 v[82:85], v[176:179], v[214:217], v[82:85]
	v_mfma_f32_16x16x32_bf16 v[134:137], v[166:169], v[188:191], v[134:137]
	v_mfma_f32_16x16x32_bf16 v[130:133], v[180:183], v[188:191], v[130:133]
	v_mfma_f32_16x16x32_bf16 v[118:121], v[166:169], v[196:199], v[118:121]
	v_mfma_f32_16x16x32_bf16 v[114:117], v[180:183], v[196:199], v[114:117]
	v_mfma_f32_16x16x32_bf16 v[102:105], v[166:169], v[210:213], v[102:105]
	v_mfma_f32_16x16x32_bf16 v[98:101], v[180:183], v[210:213], v[98:101]
	v_mfma_f32_16x16x32_bf16 v[86:89], v[166:169], v[218:221], v[86:89]
	v_mfma_f32_16x16x32_bf16 v[82:85], v[180:183], v[218:221], v[82:85]
	s_setprio 0
	s_barrier
	s_add_i32 s45, s45, s34
	v_lshl_add_u64 v[152:153], s[26:27], 0, v[0:1]
	s_mov_b32 m0, s45
	ds_read_b128 v[184:187], v174 offset:16384
	ds_read_b128 v[188:191], v174 offset:17408
	ds_read_b128 v[192:195], v174 offset:18432
	ds_read_b128 v[196:199], v174 offset:19456
	ds_read_b128 v[200:203], v174 offset:20480
	ds_read_b128 v[210:213], v174 offset:21504
	ds_read_b128 v[214:217], v174 offset:22528
	ds_read_b128 v[218:221], v174 offset:23552
	global_load_lds_dwordx4 v[152:153], off
	s_add_i32 m0, s45, 0x2000
	s_add_u32 s64, s26, 0x40000
	v_lshl_add_u64 v[222:223], s[26:27], 0, v[146:147]
	s_addc_u32 s65, s27, 0
	s_add_i32 s45, s68, s34
	global_load_lds_dwordx4 v[222:223], off
	v_lshl_add_u64 v[224:225], s[64:65], 0, v[0:1]
	s_mov_b32 m0, s45
	v_lshl_add_u64 v[226:227], s[28:29], 0, v[146:147]
	global_load_lds_dwordx4 v[224:225], off
	v_lshl_add_u64 v[224:225], s[64:65], 0, v[146:147]
	s_add_i32 m0, s45, 0x2000
	s_nop 0
	global_load_lds_dwordx4 v[224:225], off
	v_lshl_add_u64 v[224:225], s[28:29], 0, v[0:1]
	s_mov_b32 m0, s35
	s_nop 0
	global_load_lds_dwordx4 v[224:225], off
	s_mov_b32 m0, s36
	s_nop 0
	global_load_lds_dwordx4 v[226:227], off
	s_waitcnt vmcnt(8)
	s_waitcnt lgkmcnt(0)
	s_barrier
; #define PG8_STAGE(bufoff, gbase, voff) do { _Pragma("unroll") for (int _i = 0; _i < 2; ++_i) \
;         __builtin_amdgcn_global_load_lds((const unsigned*)((const char*)(gbase) + (voff)[_i]), (PG8_LAS unsigned*)(lds + (bufoff) + ldsw + _i * 8192), 16, 0, 0); } while (0)
; #define PG8_LDA(dst, b, h) do { _Pragma("unroll") for (int m = 0; m < 4; ++m) _Pragma("unroll") for (int k = 0; k < 2; ++k) dst[m][k] = *(const PG8_LAS bf16x8*)(lds + PG8_SA(b, h) + aoff + m * 2048 + k * 1024); } while (0)
; #define PG8_LDB(dst, b, h) do { _Pragma("unroll") for (int n = 0; n < 2; ++n) _Pragma("unroll") for (int k = 0; k < 2; ++k) dst[n][k] = *(const PG8_LAS bf16x8*)(lds + PG8_SB(b, h) + boff + n * 2048 + k * 1024); } while (0)
; #define PG8_MMA(ai, bj, At, Bt) do { __builtin_amdgcn_s_setprio(1); _Pragma("unroll") for (int m = 0; m < 4; ++m) _Pragma("unroll") for (int n = 0; n < 2; ++n) _Pragma("unroll") for (int k = 0; k < 2; ++k) \
;         acc[ai][bj][m][n] = __builtin_amdgcn_mfma_f32_16x16x32_bf16(Bt[n][k], At[m][k], acc[ai][bj][m][n], 0, 0, 0); __builtin_amdgcn_s_setprio(0); } while (0)
; #define PG8_WAIT_V(n) asm volatile("s_waitcnt vmcnt(" #n ")" ::: "memory")
; #define PG8_WAIT_L(n) asm volatile("s_waitcnt lgkmcnt(" #n ")" ::: "memory")
; #define PG8_BAR __builtin_amdgcn_s_barrier()
; #define PG8_SCHED __builtin_amdgcn_sched_barrier(0)
; template <class Epi, class Sched, bool ALIGN_EPI = false, bool SP2 = false>
; __device__ __forceinline__ void gemm_phase(PG8_LAS unsigned char* lds, const Gemm g, const Sched& S, const Epi& E, const int wave_s) {
;     ...
;             PG8_WAIT_V(8); PG8_WAIT_L(0); PG8_BAR; PG8_MMA(1, 0, At, B0); PG8_MMA(1, 1, At, B1); PG8_BAR; PG8_SCHED;
;             PG8_LDB(B0, 1, 0); PG8_LDB(B1, 1, 1); PG8_SCHED; PG8_LDA(At, 1, 0); PG8_STAGE(PG8_SA(0, 1), a2 + hstep, voffA);
;             PG8_WAIT_V(8); PG8_WAIT_L(0); PG8_BAR; PG8_MMA(0, 0, At, B0); PG8_MMA(0, 1, At, B1); PG8_BAR; PG8_SCHED;
	s_setprio 1
	s_waitcnt lgkmcnt(0)
	v_mfma_f32_16x16x32_bf16 v[78:81], v[26:29], v[184:187], v[78:81]
	v_mfma_f32_16x16x32_bf16 v[74:77], v[46:49], v[184:187], v[74:77]
	v_mfma_f32_16x16x32_bf16 v[62:65], v[26:29], v[192:195], v[62:65]
	v_mfma_f32_16x16x32_bf16 v[58:61], v[46:49], v[192:195], v[58:61]
	v_mfma_f32_16x16x32_bf16 v[38:41], v[26:29], v[200:203], v[38:41]
	v_mfma_f32_16x16x32_bf16 v[34:37], v[46:49], v[200:203], v[34:37]
	v_mfma_f32_16x16x32_bf16 v[14:17], v[26:29], v[214:217], v[14:17]
	v_mfma_f32_16x16x32_bf16 v[10:13], v[46:49], v[214:217], v[10:13]
	v_mfma_f32_16x16x32_bf16 v[78:81], v[30:33], v[188:191], v[78:81]
	v_mfma_f32_16x16x32_bf16 v[74:77], v[50:53], v[188:191], v[74:77]
	v_mfma_f32_16x16x32_bf16 v[62:65], v[30:33], v[196:199], v[62:65]
	v_mfma_f32_16x16x32_bf16 v[58:61], v[50:53], v[196:199], v[58:61]
	v_mfma_f32_16x16x32_bf16 v[38:41], v[30:33], v[210:213], v[38:41]
	v_mfma_f32_16x16x32_bf16 v[34:37], v[50:53], v[210:213], v[34:37]
	v_mfma_f32_16x16x32_bf16 v[14:17], v[30:33], v[218:221], v[14:17]
	v_mfma_f32_16x16x32_bf16 v[10:13], v[50:53], v[218:221], v[10:13]
	v_mfma_f32_16x16x32_bf16 v[42:45], v[176:179], v[192:195], v[42:45]
	v_mfma_f32_16x16x32_bf16 v[22:25], v[162:165], v[200:203], v[22:25]
	v_mfma_f32_16x16x32_bf16 v[18:21], v[176:179], v[200:203], v[18:21]
	v_mfma_f32_16x16x32_bf16 v[6:9], v[162:165], v[214:217], v[6:9]
	v_mfma_f32_16x16x32_bf16 v[2:5], v[176:179], v[214:217], v[2:5]
	v_mfma_f32_16x16x32_bf16 v[26:29], v[162:165], v[184:187], v[70:73]
	v_mfma_f32_16x16x32_bf16 v[30:33], v[176:179], v[184:187], v[66:69]
	v_mfma_f32_16x16x32_bf16 v[46:49], v[162:165], v[192:195], v[54:57]
	v_mfma_f32_16x16x32_bf16 v[42:45], v[180:183], v[196:199], v[42:45]
	v_mfma_f32_16x16x32_bf16 v[22:25], v[166:169], v[210:213], v[22:25]
	v_mfma_f32_16x16x32_bf16 v[18:21], v[180:183], v[210:213], v[18:21]
	v_mfma_f32_16x16x32_bf16 v[6:9], v[166:169], v[218:221], v[6:9]
	v_mfma_f32_16x16x32_bf16 v[2:5], v[180:183], v[218:221], v[2:5]
	v_mfma_f32_16x16x32_bf16 v[26:29], v[166:169], v[188:191], v[26:29]
	v_mfma_f32_16x16x32_bf16 v[30:33], v[180:183], v[188:191], v[30:33]
	v_mfma_f32_16x16x32_bf16 v[46:49], v[166:169], v[196:199], v[46:49]
	s_setprio 0
	s_barrier
	s_add_i32 s45, 0, 0x18000
	s_add_i32 s64, 0, 0x1c000
	v_add_u32_e32 v70, s45, v171
	v_add_u32_e32 v175, s64, v171
	ds_read_b128 v[50:53], v70
	ds_read_b128 v[54:57], v70 offset:1024
	ds_read_b128 v[66:69], v70 offset:2048
	ds_read_b128 v[70:73], v70 offset:3072
	ds_read_b128 v[162:165], v175
	ds_read_b128 v[166:169], v175 offset:1024
	ds_read_b128 v[176:179], v175 offset:2048
	ds_read_b128 v[180:183], v175 offset:3072
	s_add_u32 s28, s28, 0x40000
	s_addc_u32 s29, s29, 0
	s_mov_b32 m0, s37
	v_lshl_add_u64 v[228:229], s[28:29], 0, v[0:1]
	ds_read_b128 v[184:187], v174 offset:32768
	ds_read_b128 v[188:191], v174 offset:33792
	ds_read_b128 v[192:195], v174 offset:34816
	ds_read_b128 v[196:199], v174 offset:35840
	ds_read_b128 v[200:203], v174 offset:36864
	ds_read_b128 v[210:213], v174 offset:37888
	ds_read_b128 v[214:217], v174 offset:38912
	ds_read_b128 v[218:221], v174 offset:39936
	global_load_lds_dwordx4 v[228:229], off
	v_lshl_add_u64 v[228:229], s[28:29], 0, v[146:147]
	s_mov_b32 m0, s38
	s_nop 0
	global_load_lds_dwordx4 v[228:229], off
	s_waitcnt vmcnt(8)
	s_waitcnt lgkmcnt(0)
	s_barrier
	s_setprio 1
	s_waitcnt lgkmcnt(0)
	v_mfma_f32_16x16x32_bf16 v[142:145], v[50:53], v[184:187], v[142:145]
	v_mfma_f32_16x16x32_bf16 v[138:141], v[66:69], v[184:187], v[138:141]
	v_mfma_f32_16x16x32_bf16 v[126:129], v[50:53], v[192:195], v[126:129]
	v_mfma_f32_16x16x32_bf16 v[122:125], v[66:69], v[192:195], v[122:125]
	v_mfma_f32_16x16x32_bf16 v[110:113], v[50:53], v[200:203], v[110:113]
	v_mfma_f32_16x16x32_bf16 v[106:109], v[66:69], v[200:203], v[106:109]
	v_mfma_f32_16x16x32_bf16 v[94:97], v[50:53], v[214:217], v[94:97]
	v_mfma_f32_16x16x32_bf16 v[90:93], v[66:69], v[214:217], v[90:93]
	v_mfma_f32_16x16x32_bf16 v[142:145], v[54:57], v[188:191], v[142:145]
	v_mfma_f32_16x16x32_bf16 v[138:141], v[70:73], v[188:191], v[138:141]
	v_mfma_f32_16x16x32_bf16 v[126:129], v[54:57], v[196:199], v[126:129]
	v_mfma_f32_16x16x32_bf16 v[122:125], v[70:73], v[196:199], v[122:125]
	v_mfma_f32_16x16x32_bf16 v[110:113], v[54:57], v[210:213], v[110:113]
	v_mfma_f32_16x16x32_bf16 v[106:109], v[70:73], v[210:213], v[106:109]
	v_mfma_f32_16x16x32_bf16 v[94:97], v[54:57], v[218:221], v[94:97]
	v_mfma_f32_16x16x32_bf16 v[90:93], v[70:73], v[218:221], v[90:93]
	v_mfma_f32_16x16x32_bf16 v[134:137], v[162:165], v[184:187], v[134:137]
	v_mfma_f32_16x16x32_bf16 v[130:133], v[176:179], v[184:187], v[130:133]
	v_mfma_f32_16x16x32_bf16 v[118:121], v[162:165], v[192:195], v[118:121]
	v_mfma_f32_16x16x32_bf16 v[114:117], v[176:179], v[192:195], v[114:117]
	v_mfma_f32_16x16x32_bf16 v[102:105], v[162:165], v[200:203], v[102:105]
	v_mfma_f32_16x16x32_bf16 v[98:101], v[176:179], v[200:203], v[98:101]
	v_mfma_f32_16x16x32_bf16 v[86:89], v[162:165], v[214:217], v[86:89]
	v_mfma_f32_16x16x32_bf16 v[82:85], v[176:179], v[214:217], v[82:85]
	v_mfma_f32_16x16x32_bf16 v[134:137], v[166:169], v[188:191], v[134:137]
	v_mfma_f32_16x16x32_bf16 v[130:133], v[180:183], v[188:191], v[130:133]
	v_mfma_f32_16x16x32_bf16 v[118:121], v[166:169], v[196:199], v[118:121]
	v_mfma_f32_16x16x32_bf16 v[114:117], v[180:183], v[196:199], v[114:117]
	v_mfma_f32_16x16x32_bf16 v[102:105], v[166:169], v[210:213], v[102:105]
	v_mfma_f32_16x16x32_bf16 v[98:101], v[180:183], v[210:213], v[98:101]
	v_mfma_f32_16x16x32_bf16 v[86:89], v[166:169], v[218:221], v[86:89]
	v_mfma_f32_16x16x32_bf16 v[82:85], v[180:183], v[218:221], v[82:85]
	s_setprio 0
	s_barrier
; #define PG8_STAGE(bufoff, gbase, voff) do { _Pragma("unroll") for (int _i = 0; _i < 2; ++_i) \
;         __builtin_amdgcn_global_load_lds((const unsigned*)((const char*)(gbase) + (voff)[_i]), (PG8_LAS unsigned*)(lds + (bufoff) + ldsw + _i * 8192), 16, 0, 0); } while (0)
; #define PG8_LDA(dst, b, h) do { _Pragma("unroll") for (int m = 0; m < 4; ++m) _Pragma("unroll") for (int k = 0; k < 2; ++k) dst[m][k] = *(const PG8_LAS bf16x8*)(lds + PG8_SA(b, h) + aoff + m * 2048 + k * 1024); } while (0)
; #define PG8_BAR __builtin_amdgcn_s_barrier()
; template <class Epi, class Sched, bool ALIGN_EPI = false, bool SP2 = false>
; __device__ __forceinline__ void gemm_phase(PG8_LAS unsigned char* lds, const Gemm g, const Sched& S, const Epi& E, const int wave_s) {
;     ...
;             PG8_LDA(At, 1, 1); PG8_STAGE(PG8_SB(1, 0), b3, voffB); PG8_STAGE(PG8_SB(1, 1), b3 + hstep, voffB); PG8_STAGE(PG8_SA(1, 0), a3, voffA);
;             PG8_WAIT_V(8); PG8_WAIT_L(0); PG8_BAR; PG8_MMA(1, 0, At, B0); PG8_MMA(1, 1, At, B1); PG8_BAR; PG8_SCHED;
;             } else {
;             PG8_LDB(B0, 0, 0); PG8_SCHED; PG8_LDA(At, 0, 0); PG8_STAGE(PG8_SA(1, 1), a1 + hstep, voffA);
;             PG8_WAIT_L(8); PG8_BAR; PG8_WAIT_L(0); PG8_MMA(0, 0, At, B0); PG8_BAR; PG8_SCHED;
;             PG8_LDB(B1, 0, 1); PG8_STAGE(PG8_SB(0, 0), b2, voffB);
;             PG8_BAR; PG8_WAIT_L(0); PG8_MMA(0, 1, At, B1); PG8_BAR;
;             PG8_LDA(At, 0, 1); PG8_STAGE(PG8_SA(0, 0), a2, voffA);
;             PG8_BAR; PG8_WAIT_L(0); PG8_MMA(1, 0, At, B0); PG8_BAR; PG8_SCHED;
;             PG8_STAGE(PG8_SB(0, 1), b2 + hstep, voffB);
;             PG8_WAIT_V(6); PG8_BAR; PG8_MMA(1, 1, At, B1); PG8_BAR;
;             PG8_LDB(B0, 1, 0); PG8_SCHED; PG8_LDA(At, 1, 0); PG8_STAGE(PG8_SA(0, 1), a2 + hstep, voffA);
;             PG8_WAIT_L(8); PG8_BAR; PG8_WAIT_L(0); PG8_MMA(0, 0, At, B0); PG8_BAR; PG8_SCHED;
;             PG8_LDB(B1, 1, 1); PG8_STAGE(PG8_SB(1, 0), b3, voffB);
;             PG8_BAR; PG8_WAIT_L(0); PG8_MMA(0, 1, At, B1); PG8_BAR;
;             PG8_LDA(At, 1, 1); PG8_STAGE(PG8_SA(1, 0), a3, voffA);
;             PG8_BAR; PG8_WAIT_L(0); PG8_MMA(1, 0, At, B0); PG8_BAR; PG8_SCHED;
;             PG8_STAGE(PG8_SB(1, 1), b3 + hstep, voffB);
;             PG8_WAIT_V(6); PG8_BAR; PG8_MMA(1, 1, At, B1); PG8_BAR;
;             }
;         }
;         if constexpr (ALIGN_EPI) { if (wr == 0) PG8_BAR; }
	s_add_i32 s28, s45, s34
	v_lshl_add_u64 v[152:153], v[152:153], 0, s[70:71]
	s_mov_b32 m0, s28
	ds_read_b128 v[184:187], v174 offset:49152
	ds_read_b128 v[188:191], v174 offset:50176
	ds_read_b128 v[192:195], v174 offset:51200
	ds_read_b128 v[196:199], v174 offset:52224
	ds_read_b128 v[200:203], v174 offset:53248
	ds_read_b128 v[210:213], v174 offset:54272
	ds_read_b128 v[214:217], v174 offset:55296
	ds_read_b128 v[218:221], v174 offset:56320
	global_load_lds_dwordx4 v[152:153], off
	s_add_i32 m0, s28, 0x2000
	s_add_u32 s26, s26, 0x40080
	v_lshl_add_u64 v[152:153], v[222:223], 0, s[70:71]
	s_addc_u32 s27, s27, 0
	s_add_i32 s28, s64, s34
	global_load_lds_dwordx4 v[152:153], off
	v_lshl_add_u64 v[152:153], s[26:27], 0, v[0:1]
	s_mov_b32 m0, s28
	s_nop 0
	global_load_lds_dwordx4 v[152:153], off
	v_lshl_add_u64 v[152:153], s[26:27], 0, v[146:147]
	s_add_i32 m0, s28, 0x2000
	s_nop 0
	global_load_lds_dwordx4 v[152:153], off
	v_lshl_add_u64 v[152:153], v[224:225], 0, s[70:71]
	s_mov_b32 m0, s40
	s_nop 0
	global_load_lds_dwordx4 v[152:153], off
	v_lshl_add_u64 v[152:153], v[226:227], 0, s[70:71]
	s_mov_b32 m0, s41
	s_nop 0
	global_load_lds_dwordx4 v[152:153], off
	s_waitcnt vmcnt(8)
	s_waitcnt lgkmcnt(0)
	s_barrier
	s_setprio 1
	s_waitcnt lgkmcnt(0)
	v_mfma_f32_16x16x32_bf16 v[78:81], v[50:53], v[184:187], v[78:81]
	v_mfma_f32_16x16x32_bf16 v[74:77], v[66:69], v[184:187], v[74:77]
	v_mfma_f32_16x16x32_bf16 v[62:65], v[50:53], v[192:195], v[62:65]
	v_mfma_f32_16x16x32_bf16 v[58:61], v[66:69], v[192:195], v[58:61]
	v_mfma_f32_16x16x32_bf16 v[38:41], v[50:53], v[200:203], v[38:41]
	v_mfma_f32_16x16x32_bf16 v[34:37], v[66:69], v[200:203], v[34:37]
	v_mfma_f32_16x16x32_bf16 v[14:17], v[50:53], v[214:217], v[14:17]
	v_mfma_f32_16x16x32_bf16 v[10:13], v[66:69], v[214:217], v[10:13]
	v_mfma_f32_16x16x32_bf16 v[78:81], v[54:57], v[188:191], v[78:81]
	v_mfma_f32_16x16x32_bf16 v[74:77], v[70:73], v[188:191], v[74:77]
	v_mfma_f32_16x16x32_bf16 v[62:65], v[54:57], v[196:199], v[62:65]
	v_mfma_f32_16x16x32_bf16 v[58:61], v[70:73], v[196:199], v[58:61]
	v_mfma_f32_16x16x32_bf16 v[38:41], v[54:57], v[210:213], v[38:41]
	v_mfma_f32_16x16x32_bf16 v[34:37], v[70:73], v[210:213], v[34:37]
	v_mfma_f32_16x16x32_bf16 v[14:17], v[54:57], v[218:221], v[14:17]
	v_mfma_f32_16x16x32_bf16 v[10:13], v[70:73], v[218:221], v[10:13]
	v_mfma_f32_16x16x32_bf16 v[26:29], v[162:165], v[184:187], v[26:29]
	v_mfma_f32_16x16x32_bf16 v[70:73], v[166:169], v[188:191], v[26:29]
	v_mfma_f32_16x16x32_bf16 v[26:29], v[176:179], v[184:187], v[30:33]
	v_mfma_f32_16x16x32_bf16 v[66:69], v[180:183], v[188:191], v[26:29]
	v_mfma_f32_16x16x32_bf16 v[26:29], v[162:165], v[192:195], v[46:49]
	v_mfma_f32_16x16x32_bf16 v[54:57], v[166:169], v[196:199], v[26:29]
	v_mfma_f32_16x16x32_bf16 v[26:29], v[176:179], v[192:195], v[42:45]
	v_mfma_f32_16x16x32_bf16 v[22:25], v[162:165], v[200:203], v[22:25]
	v_mfma_f32_16x16x32_bf16 v[18:21], v[176:179], v[200:203], v[18:21]
	v_mfma_f32_16x16x32_bf16 v[6:9], v[162:165], v[214:217], v[6:9]
	v_mfma_f32_16x16x32_bf16 v[2:5], v[176:179], v[214:217], v[2:5]
	v_mfma_f32_16x16x32_bf16 v[42:45], v[180:183], v[196:199], v[26:29]
	v_mfma_f32_16x16x32_bf16 v[22:25], v[166:169], v[210:213], v[22:25]
	v_mfma_f32_16x16x32_bf16 v[18:21], v[180:183], v[210:213], v[18:21]
	v_mfma_f32_16x16x32_bf16 v[6:9], v[166:169], v[218:221], v[6:9]
	v_mfma_f32_16x16x32_bf16 v[2:5], v[180:183], v[218:221], v[2:5]
	s_setprio 0
	s_barrier
	s_add_i32 s50, s50, 2
	s_add_u32 s24, s24, 0x100
	s_addc_u32 s25, s25, 0
	s_add_u32 s58, s58, 0x100
	s_addc_u32 s59, s59, 0
	s_cmp_gt_u32 s50, 13
	s_cbranch_scc0 .LBB0_734
	s_and_b64 vcc, exec, s[14:15]
	s_cbranch_vccz .LBB0_737
	s_barrier

; #define PG8_STAGE(bufoff, gbase, voff) do { _Pragma("unroll") for (int _i = 0; _i < 2; ++_i) \
;         __builtin_amdgcn_global_load_lds((const unsigned*)((const char*)(gbase) + (voff)[_i]), (PG8_LAS unsigned*)(lds + (bufoff) + ldsw + _i * 8192), 16, 0, 0); } while (0)
; #define PG8_LDA(dst, b, h) do { _Pragma("unroll") for (int m = 0; m < 4; ++m) _Pragma("unroll") for (int k = 0; k < 2; ++k) dst[m][k] = *(const PG8_LAS bf16x8*)(lds + PG8_SA(b, h) + aoff + m * 2048 + k * 1024); } while (0)
; #define PG8_LDB(dst, b, h) do { _Pragma("unroll") for (int n = 0; n < 2; ++n) _Pragma("unroll") for (int k = 0; k < 2; ++k) dst[n][k] = *(const PG8_LAS bf16x8*)(lds + PG8_SB(b, h) + boff + n * 2048 + k * 1024); } while (0)
; #define PG8_MMA(ai, bj, At, Bt) do { __builtin_amdgcn_s_setprio(1); _Pragma("unroll") for (int m = 0; m < 4; ++m) _Pragma("unroll") for (int n = 0; n < 2; ++n) _Pragma("unroll") for (int k = 0; k < 2; ++k) \
;         acc[ai][bj][m][n] = __builtin_amdgcn_mfma_f32_16x16x32_bf16(Bt[n][k], At[m][k], acc[ai][bj][m][n], 0, 0, 0); __builtin_amdgcn_s_setprio(0); } while (0)
; #define PG8_WAIT_V(n) asm volatile("s_waitcnt vmcnt(" #n ")" ::: "memory")
; #define PG8_WAIT_L(n) asm volatile("s_waitcnt lgkmcnt(" #n ")" ::: "memory")
; template <class Epi, class Sched, bool ALIGN_EPI = false, bool SP2 = false>
; __device__ __forceinline__ void gemm_phase(PG8_LAS unsigned char* lds, const Gemm g, const Sched& S, const Epi& E, const int wave_s) {
;     ...
;             const bool last = (t == nt - 2);
;             const char* a1 = cA + (size_t)(t + 1) * kstep;
;             const char* a2 = last ? nA : cA + (size_t)(t + 2) * kstep; const char* b2 = last ? nB : cB + (size_t)(t + 2) * kstep;
;             const char* a3 = a2 + kstep; const char* b3 = b2 + kstep;
;             if (last && has_next) S.a_ready(nxt);
;             if constexpr (SP2) {
;             PG8_LDB(B0, 0, 0); PG8_LDB(B1, 0, 1); PG8_SCHED; PG8_LDA(At, 0, 0); PG8_STAGE(PG8_SA(1, 1), a1 + hstep, voffA);
;             PG8_WAIT_V(8); PG8_WAIT_L(0); PG8_BAR; PG8_MMA(0, 0, At, B0); PG8_MMA(0, 1, At, B1); PG8_BAR; PG8_SCHED;
;             PG8_LDA(At, 0, 1); PG8_STAGE(PG8_SB(0, 0), b2, voffB); PG8_STAGE(PG8_SB(0, 1), b2 + hstep, voffB); PG8_STAGE(PG8_SA(0, 0), a2, voffA);
;             PG8_WAIT_V(8); PG8_WAIT_L(0); PG8_BAR; PG8_MMA(1, 0, At, B0); PG8_MMA(1, 1, At, B1); PG8_BAR; PG8_SCHED;
.LBB0_806:
	s_add_u32 s8, s10, 0x100
	s_addc_u32 s9, s11, 0
	s_add_i32 s45, 0, 0x10000
	s_cmp_eq_u32 s75, 40
	s_cselect_b32 s49, s37, s9
	s_cselect_b32 s48, s36, s8
	v_add_u32_e32 v0, s45, v203
	s_cselect_b32 s41, s39, vcc_hi
	s_cselect_b32 s40, s38, vcc_lo
	s_add_i32 s80, 0, 0x14000
	ds_read_b128 v[122:125], v0
	ds_read_b128 v[126:129], v0 offset:1024
	ds_read_b128 v[138:141], v0 offset:2048
	ds_read_b128 v[142:145], v0 offset:3072
	v_add_u32_e32 v0, s80, v203
	ds_read_b128 v[146:149], v0
	ds_read_b128 v[150:153], v0 offset:1024
	ds_read_b128 v[174:177], v0 offset:2048
	ds_read_b128 v[178:181], v0 offset:3072
	v_lshl_add_u64 v[226:227], s[10:11], 0, v[170:171]
	s_add_i32 m0, s76, 0xc000
	ds_read_b128 v[182:185], v212
	ds_read_b128 v[186:189], v212 offset:1024
	ds_read_b128 v[190:193], v212 offset:2048
	ds_read_b128 v[194:197], v212 offset:3072
	ds_read_b128 v[198:201], v212 offset:4096
	ds_read_b128 v[214:217], v212 offset:5120
	ds_read_b128 v[218:221], v212 offset:6144
	ds_read_b128 v[222:225], v212 offset:7168
	global_load_lds_dwordx4 v[226:227], off
	v_lshl_add_u64 v[226:227], s[10:11], 0, v[172:173]
	s_add_i32 m0, s76, 0xe000
	s_nop 0
	global_load_lds_dwordx4 v[226:227], off
	s_waitcnt vmcnt(8)
	s_waitcnt lgkmcnt(0)
	s_barrier
	s_setprio 1
	s_waitcnt lgkmcnt(0)
	v_mfma_f32_16x16x32_bf16 v[6:9], v[122:125], v[182:185], v[6:9]
	v_mfma_f32_16x16x32_bf16 v[2:5], v[138:141], v[182:185], v[2:5]
	v_mfma_f32_16x16x32_bf16 v[134:137], v[122:125], v[190:193], v[134:137]
	v_mfma_f32_16x16x32_bf16 v[130:133], v[138:141], v[190:193], v[130:133]
	v_mfma_f32_16x16x32_bf16 v[118:121], v[122:125], v[198:201], v[118:121]
	v_mfma_f32_16x16x32_bf16 v[114:117], v[138:141], v[198:201], v[114:117]
	v_mfma_f32_16x16x32_bf16 v[110:113], v[122:125], v[218:221], v[110:113]
	v_mfma_f32_16x16x32_bf16 v[106:109], v[138:141], v[218:221], v[106:109]
	v_mfma_f32_16x16x32_bf16 v[6:9], v[126:129], v[186:189], v[6:9]
	v_mfma_f32_16x16x32_bf16 v[2:5], v[142:145], v[186:189], v[2:5]
	v_mfma_f32_16x16x32_bf16 v[134:137], v[126:129], v[194:197], v[134:137]
	v_mfma_f32_16x16x32_bf16 v[130:133], v[142:145], v[194:197], v[130:133]
	v_mfma_f32_16x16x32_bf16 v[118:121], v[126:129], v[214:217], v[118:121]
	v_mfma_f32_16x16x32_bf16 v[114:117], v[142:145], v[214:217], v[114:117]
	v_mfma_f32_16x16x32_bf16 v[110:113], v[126:129], v[222:225], v[110:113]
	v_mfma_f32_16x16x32_bf16 v[106:109], v[142:145], v[222:225], v[106:109]
	v_mfma_f32_16x16x32_bf16 v[70:73], v[146:149], v[182:185], v[70:73]
	v_mfma_f32_16x16x32_bf16 v[66:69], v[174:177], v[182:185], v[66:69]
	v_mfma_f32_16x16x32_bf16 v[62:65], v[146:149], v[190:193], v[62:65]
	v_mfma_f32_16x16x32_bf16 v[58:61], v[174:177], v[190:193], v[58:61]
	v_mfma_f32_16x16x32_bf16 v[54:57], v[146:149], v[198:201], v[54:57]
	v_mfma_f32_16x16x32_bf16 v[50:53], v[174:177], v[198:201], v[50:53]
	v_mfma_f32_16x16x32_bf16 v[46:49], v[146:149], v[218:221], v[46:49]
	v_mfma_f32_16x16x32_bf16 v[42:45], v[174:177], v[218:221], v[42:45]
	v_mfma_f32_16x16x32_bf16 v[70:73], v[150:153], v[186:189], v[70:73]
	v_mfma_f32_16x16x32_bf16 v[66:69], v[178:181], v[186:189], v[66:69]
	v_mfma_f32_16x16x32_bf16 v[62:65], v[150:153], v[194:197], v[62:65]
	v_mfma_f32_16x16x32_bf16 v[58:61], v[178:181], v[194:197], v[58:61]
	v_mfma_f32_16x16x32_bf16 v[54:57], v[150:153], v[214:217], v[54:57]
	v_mfma_f32_16x16x32_bf16 v[50:53], v[178:181], v[214:217], v[50:53]
	v_mfma_f32_16x16x32_bf16 v[46:49], v[150:153], v[222:225], v[46:49]
	v_mfma_f32_16x16x32_bf16 v[42:45], v[178:181], v[222:225], v[42:45]
	s_setprio 0
	s_barrier
	s_add_i32 s10, s45, s44
	v_lshl_add_u64 v[226:227], s[40:41], 0, v[166:167]
	s_mov_b32 m0, s10
	ds_read_b128 v[182:185], v212 offset:16384
	ds_read_b128 v[186:189], v212 offset:17408
	ds_read_b128 v[190:193], v212 offset:18432
	ds_read_b128 v[194:197], v212 offset:19456
	ds_read_b128 v[198:201], v212 offset:20480
	ds_read_b128 v[214:217], v212 offset:21504
	ds_read_b128 v[218:221], v212 offset:22528
	ds_read_b128 v[222:225], v212 offset:23552
	global_load_lds_dwordx4 v[226:227], off
	s_add_i32 m0, s10, 0x2000
	s_add_u32 s10, s40, 0xb0000
	v_lshl_add_u64 v[228:229], s[40:41], 0, v[162:163]
	s_addc_u32 s11, s41, 0
	s_add_i32 s45, s80, s44
	global_load_lds_dwordx4 v[228:229], off
	v_lshl_add_u64 v[230:231], s[10:11], 0, v[166:167]
	s_mov_b32 m0, s45
	v_lshl_add_u64 v[232:233], s[48:49], 0, v[164:165]
	global_load_lds_dwordx4 v[230:231], off
	v_lshl_add_u64 v[230:231], s[10:11], 0, v[162:163]
	s_add_i32 m0, s45, 0x2000
	s_nop 0
	global_load_lds_dwordx4 v[230:231], off
	v_lshl_add_u64 v[230:231], s[48:49], 0, v[168:169]
	s_mov_b32 m0, s76
	s_nop 0
	global_load_lds_dwordx4 v[230:231], off
	s_mov_b32 m0, s77
	s_nop 0
	global_load_lds_dwordx4 v[232:233], off
	s_waitcnt vmcnt(8)
	s_waitcnt lgkmcnt(0)
	s_barrier
; #define PG8_STAGE(bufoff, gbase, voff) do { _Pragma("unroll") for (int _i = 0; _i < 2; ++_i) \
;         __builtin_amdgcn_global_load_lds((const unsigned*)((const char*)(gbase) + (voff)[_i]), (PG8_LAS unsigned*)(lds + (bufoff) + ldsw + _i * 8192), 16, 0, 0); } while (0)
; #define PG8_LDA(dst, b, h) do { _Pragma("unroll") for (int m = 0; m < 4; ++m) _Pragma("unroll") for (int k = 0; k < 2; ++k) dst[m][k] = *(const PG8_LAS bf16x8*)(lds + PG8_SA(b, h) + aoff + m * 2048 + k * 1024); } while (0)
; #define PG8_LDB(dst, b, h) do { _Pragma("unroll") for (int n = 0; n < 2; ++n) _Pragma("unroll") for (int k = 0; k < 2; ++k) dst[n][k] = *(const PG8_LAS bf16x8*)(lds + PG8_SB(b, h) + boff + n * 2048 + k * 1024); } while (0)
; #define PG8_MMA(ai, bj, At, Bt) do { __builtin_amdgcn_s_setprio(1); _Pragma("unroll") for (int m = 0; m < 4; ++m) _Pragma("unroll") for (int n = 0; n < 2; ++n) _Pragma("unroll") for (int k = 0; k < 2; ++k) \
;         acc[ai][bj][m][n] = __builtin_amdgcn_mfma_f32_16x16x32_bf16(Bt[n][k], At[m][k], acc[ai][bj][m][n], 0, 0, 0); __builtin_amdgcn_s_setprio(0); } while (0)
; #define PG8_WAIT_V(n) asm volatile("s_waitcnt vmcnt(" #n ")" ::: "memory")
; #define PG8_WAIT_L(n) asm volatile("s_waitcnt lgkmcnt(" #n ")" ::: "memory")
; #define PG8_BAR __builtin_amdgcn_s_barrier()
; #define PG8_SCHED __builtin_amdgcn_sched_barrier(0)
; template <class Epi, class Sched, bool ALIGN_EPI = false, bool SP2 = false>
; __device__ __forceinline__ void gemm_phase(PG8_LAS unsigned char* lds, const Gemm g, const Sched& S, const Epi& E, const int wave_s) {
;     ...
;             PG8_WAIT_V(8); PG8_WAIT_L(0); PG8_BAR; PG8_MMA(1, 0, At, B0); PG8_MMA(1, 1, At, B1); PG8_BAR; PG8_SCHED;
;             PG8_LDB(B0, 1, 0); PG8_LDB(B1, 1, 1); PG8_SCHED; PG8_LDA(At, 1, 0); PG8_STAGE(PG8_SA(0, 1), a2 + hstep, voffA);
;             PG8_WAIT_V(8); PG8_WAIT_L(0); PG8_BAR; PG8_MMA(0, 0, At, B0); PG8_MMA(0, 1, At, B1); PG8_BAR; PG8_SCHED;
	s_setprio 1
	s_waitcnt lgkmcnt(0)
	v_mfma_f32_16x16x32_bf16 v[102:105], v[122:125], v[182:185], v[102:105]
	v_mfma_f32_16x16x32_bf16 v[98:101], v[138:141], v[182:185], v[98:101]
	v_mfma_f32_16x16x32_bf16 v[94:97], v[122:125], v[190:193], v[94:97]
	v_mfma_f32_16x16x32_bf16 v[90:93], v[138:141], v[190:193], v[90:93]
	v_mfma_f32_16x16x32_bf16 v[86:89], v[122:125], v[198:201], v[86:89]
	v_mfma_f32_16x16x32_bf16 v[82:85], v[138:141], v[198:201], v[82:85]
	v_mfma_f32_16x16x32_bf16 v[78:81], v[122:125], v[218:221], v[78:81]
	v_mfma_f32_16x16x32_bf16 v[74:77], v[138:141], v[218:221], v[74:77]
	v_mfma_f32_16x16x32_bf16 v[102:105], v[126:129], v[186:189], v[102:105]
	v_mfma_f32_16x16x32_bf16 v[98:101], v[142:145], v[186:189], v[98:101]
	v_mfma_f32_16x16x32_bf16 v[94:97], v[126:129], v[194:197], v[94:97]
	v_mfma_f32_16x16x32_bf16 v[90:93], v[142:145], v[194:197], v[90:93]
	v_mfma_f32_16x16x32_bf16 v[86:89], v[126:129], v[214:217], v[86:89]
	v_mfma_f32_16x16x32_bf16 v[82:85], v[142:145], v[214:217], v[82:85]
	v_mfma_f32_16x16x32_bf16 v[78:81], v[126:129], v[222:225], v[78:81]
	v_mfma_f32_16x16x32_bf16 v[74:77], v[142:145], v[222:225], v[74:77]
	v_mfma_f32_16x16x32_bf16 v[38:41], v[146:149], v[182:185], v[38:41]
	v_mfma_f32_16x16x32_bf16 v[34:37], v[174:177], v[182:185], v[34:37]
	v_mfma_f32_16x16x32_bf16 v[30:33], v[146:149], v[190:193], v[30:33]
	v_mfma_f32_16x16x32_bf16 v[26:29], v[174:177], v[190:193], v[26:29]
	v_mfma_f32_16x16x32_bf16 v[22:25], v[146:149], v[198:201], v[22:25]
	v_mfma_f32_16x16x32_bf16 v[18:21], v[174:177], v[198:201], v[18:21]
	v_mfma_f32_16x16x32_bf16 v[14:17], v[146:149], v[218:221], v[14:17]
	v_mfma_f32_16x16x32_bf16 v[10:13], v[174:177], v[218:221], v[10:13]
	v_mfma_f32_16x16x32_bf16 v[38:41], v[150:153], v[186:189], v[38:41]
	v_mfma_f32_16x16x32_bf16 v[34:37], v[178:181], v[186:189], v[34:37]
	v_mfma_f32_16x16x32_bf16 v[30:33], v[150:153], v[194:197], v[30:33]
	v_mfma_f32_16x16x32_bf16 v[26:29], v[178:181], v[194:197], v[26:29]
	v_mfma_f32_16x16x32_bf16 v[22:25], v[150:153], v[214:217], v[22:25]
	v_mfma_f32_16x16x32_bf16 v[18:21], v[178:181], v[214:217], v[18:21]
	v_mfma_f32_16x16x32_bf16 v[14:17], v[150:153], v[222:225], v[14:17]
	v_mfma_f32_16x16x32_bf16 v[10:13], v[178:181], v[222:225], v[10:13]
	s_setprio 0
	s_barrier
	s_add_i32 s45, 0, 0x18000
	v_add_u32_e32 v0, s45, v203
	s_add_i32 s80, 0, 0x1c000
	ds_read_b128 v[122:125], v0
	ds_read_b128 v[126:129], v0 offset:1024
	ds_read_b128 v[138:141], v0 offset:2048
	ds_read_b128 v[142:145], v0 offset:3072
	v_add_u32_e32 v0, s80, v203
	ds_read_b128 v[146:149], v0
	ds_read_b128 v[150:153], v0 offset:1024
	ds_read_b128 v[174:177], v0 offset:2048
	ds_read_b128 v[178:181], v0 offset:3072
	s_add_u32 s10, s48, 0xb0000
	s_addc_u32 s11, s49, 0
	s_mov_b32 m0, s88
	v_lshl_add_u64 v[234:235], s[10:11], 0, v[168:169]
	ds_read_b128 v[182:185], v212 offset:32768
	ds_read_b128 v[186:189], v212 offset:33792
	ds_read_b128 v[190:193], v212 offset:34816
	ds_read_b128 v[194:197], v212 offset:35840
	ds_read_b128 v[198:201], v212 offset:36864
	ds_read_b128 v[214:217], v212 offset:37888
	ds_read_b128 v[218:221], v212 offset:38912
	ds_read_b128 v[222:225], v212 offset:39936
	global_load_lds_dwordx4 v[234:235], off
	v_lshl_add_u64 v[234:235], s[10:11], 0, v[164:165]
	s_mov_b32 m0, s89
	s_nop 0
	global_load_lds_dwordx4 v[234:235], off
	s_waitcnt vmcnt(8)
	s_waitcnt lgkmcnt(0)
	s_barrier
	s_setprio 1
	s_waitcnt lgkmcnt(0)
	v_mfma_f32_16x16x32_bf16 v[6:9], v[122:125], v[182:185], v[6:9]
	v_mfma_f32_16x16x32_bf16 v[2:5], v[138:141], v[182:185], v[2:5]
	v_mfma_f32_16x16x32_bf16 v[134:137], v[122:125], v[190:193], v[134:137]
	v_mfma_f32_16x16x32_bf16 v[130:133], v[138:141], v[190:193], v[130:133]
	v_mfma_f32_16x16x32_bf16 v[118:121], v[122:125], v[198:201], v[118:121]
	v_mfma_f32_16x16x32_bf16 v[114:117], v[138:141], v[198:201], v[114:117]
	v_mfma_f32_16x16x32_bf16 v[110:113], v[122:125], v[218:221], v[110:113]
	v_mfma_f32_16x16x32_bf16 v[106:109], v[138:141], v[218:221], v[106:109]
	v_mfma_f32_16x16x32_bf16 v[6:9], v[126:129], v[186:189], v[6:9]
	v_mfma_f32_16x16x32_bf16 v[2:5], v[142:145], v[186:189], v[2:5]
	v_mfma_f32_16x16x32_bf16 v[134:137], v[126:129], v[194:197], v[134:137]
	v_mfma_f32_16x16x32_bf16 v[130:133], v[142:145], v[194:197], v[130:133]
	v_mfma_f32_16x16x32_bf16 v[118:121], v[126:129], v[214:217], v[118:121]
	v_mfma_f32_16x16x32_bf16 v[114:117], v[142:145], v[214:217], v[114:117]
	v_mfma_f32_16x16x32_bf16 v[110:113], v[126:129], v[222:225], v[110:113]
	v_mfma_f32_16x16x32_bf16 v[106:109], v[142:145], v[222:225], v[106:109]
	v_mfma_f32_16x16x32_bf16 v[70:73], v[146:149], v[182:185], v[70:73]
	v_mfma_f32_16x16x32_bf16 v[66:69], v[174:177], v[182:185], v[66:69]
	v_mfma_f32_16x16x32_bf16 v[62:65], v[146:149], v[190:193], v[62:65]
	v_mfma_f32_16x16x32_bf16 v[58:61], v[174:177], v[190:193], v[58:61]
	v_mfma_f32_16x16x32_bf16 v[54:57], v[146:149], v[198:201], v[54:57]
	v_mfma_f32_16x16x32_bf16 v[50:53], v[174:177], v[198:201], v[50:53]
	v_mfma_f32_16x16x32_bf16 v[46:49], v[146:149], v[218:221], v[46:49]
	v_mfma_f32_16x16x32_bf16 v[42:45], v[174:177], v[218:221], v[42:45]
	v_mfma_f32_16x16x32_bf16 v[70:73], v[150:153], v[186:189], v[70:73]
	v_mfma_f32_16x16x32_bf16 v[66:69], v[178:181], v[186:189], v[66:69]
	v_mfma_f32_16x16x32_bf16 v[62:65], v[150:153], v[194:197], v[62:65]
	v_mfma_f32_16x16x32_bf16 v[58:61], v[178:181], v[194:197], v[58:61]
	v_mfma_f32_16x16x32_bf16 v[54:57], v[150:153], v[214:217], v[54:57]
	v_mfma_f32_16x16x32_bf16 v[50:53], v[178:181], v[214:217], v[50:53]
	v_mfma_f32_16x16x32_bf16 v[46:49], v[150:153], v[222:225], v[46:49]
	v_mfma_f32_16x16x32_bf16 v[42:45], v[178:181], v[222:225], v[42:45]
	s_setprio 0
	s_barrier
; #define PG8_STAGE(bufoff, gbase, voff) do { _Pragma("unroll") for (int _i = 0; _i < 2; ++_i) \
;         __builtin_amdgcn_global_load_lds((const unsigned*)((const char*)(gbase) + (voff)[_i]), (PG8_LAS unsigned*)(lds + (bufoff) + ldsw + _i * 8192), 16, 0, 0); } while (0)
; #define PG8_LDA(dst, b, h) do { _Pragma("unroll") for (int m = 0; m < 4; ++m) _Pragma("unroll") for (int k = 0; k < 2; ++k) dst[m][k] = *(const PG8_LAS bf16x8*)(lds + PG8_SA(b, h) + aoff + m * 2048 + k * 1024); } while (0)
; #define PG8_BAR __builtin_amdgcn_s_barrier()
; template <class Epi, class Sched, bool ALIGN_EPI = false, bool SP2 = false>
; __device__ __forceinline__ void gemm_phase(PG8_LAS unsigned char* lds, const Gemm g, const Sched& S, const Epi& E, const int wave_s) {
;     ...
;             PG8_LDA(At, 1, 1); PG8_STAGE(PG8_SB(1, 0), b3, voffB); PG8_STAGE(PG8_SB(1, 1), b3 + hstep, voffB); PG8_STAGE(PG8_SA(1, 0), a3, voffA);
;             PG8_WAIT_V(8); PG8_WAIT_L(0); PG8_BAR; PG8_MMA(1, 0, At, B0); PG8_MMA(1, 1, At, B1); PG8_BAR; PG8_SCHED;
;             } else {
;             PG8_LDB(B0, 0, 0); PG8_SCHED; PG8_LDA(At, 0, 0); PG8_STAGE(PG8_SA(1, 1), a1 + hstep, voffA);
;             PG8_WAIT_L(8); PG8_BAR; PG8_WAIT_L(0); PG8_MMA(0, 0, At, B0); PG8_BAR; PG8_SCHED;
;             PG8_LDB(B1, 0, 1); PG8_STAGE(PG8_SB(0, 0), b2, voffB);
;             PG8_BAR; PG8_WAIT_L(0); PG8_MMA(0, 1, At, B1); PG8_BAR;
;             PG8_LDA(At, 0, 1); PG8_STAGE(PG8_SA(0, 0), a2, voffA);
;             PG8_BAR; PG8_WAIT_L(0); PG8_MMA(1, 0, At, B0); PG8_BAR; PG8_SCHED;
;             PG8_STAGE(PG8_SB(0, 1), b2 + hstep, voffB);
;             PG8_WAIT_V(6); PG8_BAR; PG8_MMA(1, 1, At, B1); PG8_BAR;
;             PG8_LDB(B0, 1, 0); PG8_SCHED; PG8_LDA(At, 1, 0); PG8_STAGE(PG8_SA(0, 1), a2 + hstep, voffA);
;             PG8_WAIT_L(8); PG8_BAR; PG8_WAIT_L(0); PG8_MMA(0, 0, At, B0); PG8_BAR; PG8_SCHED;
;             PG8_LDB(B1, 1, 1); PG8_STAGE(PG8_SB(1, 0), b3, voffB);
;             PG8_BAR; PG8_WAIT_L(0); PG8_MMA(0, 1, At, B1); PG8_BAR;
;             PG8_LDA(At, 1, 1); PG8_STAGE(PG8_SA(1, 0), a3, voffA);
;             PG8_BAR; PG8_WAIT_L(0); PG8_MMA(1, 0, At, B0); PG8_BAR; PG8_SCHED;
;             PG8_STAGE(PG8_SB(1, 1), b3 + hstep, voffB);
;             PG8_WAIT_V(6); PG8_BAR; PG8_MMA(1, 1, At, B1); PG8_BAR;
;             }
;         }
;         if constexpr (ALIGN_EPI) { if (wr == 0) PG8_BAR; }
	s_add_i32 s10, s45, s44
	v_lshl_add_u64 v[226:227], v[226:227], 0, s[70:71]
	s_mov_b32 m0, s10
	ds_read_b128 v[182:185], v212 offset:49152
	ds_read_b128 v[186:189], v212 offset:50176
	ds_read_b128 v[190:193], v212 offset:51200
	ds_read_b128 v[194:197], v212 offset:52224
	ds_read_b128 v[198:201], v212 offset:53248
	ds_read_b128 v[214:217], v212 offset:54272
	ds_read_b128 v[218:221], v212 offset:55296
	ds_read_b128 v[222:225], v212 offset:56320
	global_load_lds_dwordx4 v[226:227], off
	s_add_i32 m0, s10, 0x2000
	s_add_u32 s10, s40, 0xb0080
	v_lshl_add_u64 v[226:227], v[228:229], 0, s[70:71]
	s_addc_u32 s11, s41, 0
	s_add_i32 s40, s80, s44
	global_load_lds_dwordx4 v[226:227], off
	v_lshl_add_u64 v[226:227], s[10:11], 0, v[166:167]
	s_mov_b32 m0, s40
	s_nop 0
	global_load_lds_dwordx4 v[226:227], off
	v_lshl_add_u64 v[226:227], s[10:11], 0, v[162:163]
	s_add_i32 m0, s40, 0x2000
	s_nop 0
	global_load_lds_dwordx4 v[226:227], off
	v_lshl_add_u64 v[226:227], v[230:231], 0, s[70:71]
	s_mov_b32 m0, s62
	s_nop 0
	global_load_lds_dwordx4 v[226:227], off
	v_lshl_add_u64 v[226:227], v[232:233], 0, s[70:71]
	s_mov_b32 m0, s68
	s_nop 0
	global_load_lds_dwordx4 v[226:227], off
	s_waitcnt vmcnt(8)
	s_waitcnt lgkmcnt(0)
	s_barrier
	s_setprio 1
	s_waitcnt lgkmcnt(0)
	v_mfma_f32_16x16x32_bf16 v[102:105], v[122:125], v[182:185], v[102:105]
	v_mfma_f32_16x16x32_bf16 v[98:101], v[138:141], v[182:185], v[98:101]
	v_mfma_f32_16x16x32_bf16 v[94:97], v[122:125], v[190:193], v[94:97]
	v_mfma_f32_16x16x32_bf16 v[90:93], v[138:141], v[190:193], v[90:93]
	v_mfma_f32_16x16x32_bf16 v[86:89], v[122:125], v[198:201], v[86:89]
	v_mfma_f32_16x16x32_bf16 v[82:85], v[138:141], v[198:201], v[82:85]
	v_mfma_f32_16x16x32_bf16 v[78:81], v[122:125], v[218:221], v[78:81]
	v_mfma_f32_16x16x32_bf16 v[74:77], v[138:141], v[218:221], v[74:77]
	v_mfma_f32_16x16x32_bf16 v[102:105], v[126:129], v[186:189], v[102:105]
	v_mfma_f32_16x16x32_bf16 v[98:101], v[142:145], v[186:189], v[98:101]
	v_mfma_f32_16x16x32_bf16 v[94:97], v[126:129], v[194:197], v[94:97]
	v_mfma_f32_16x16x32_bf16 v[90:93], v[142:145], v[194:197], v[90:93]
	v_mfma_f32_16x16x32_bf16 v[86:89], v[126:129], v[214:217], v[86:89]
	v_mfma_f32_16x16x32_bf16 v[82:85], v[142:145], v[214:217], v[82:85]
	v_mfma_f32_16x16x32_bf16 v[78:81], v[126:129], v[222:225], v[78:81]
	v_mfma_f32_16x16x32_bf16 v[74:77], v[142:145], v[222:225], v[74:77]
	v_mfma_f32_16x16x32_bf16 v[38:41], v[146:149], v[182:185], v[38:41]
	v_mfma_f32_16x16x32_bf16 v[34:37], v[174:177], v[182:185], v[34:37]
	v_mfma_f32_16x16x32_bf16 v[30:33], v[146:149], v[190:193], v[30:33]
	v_mfma_f32_16x16x32_bf16 v[26:29], v[174:177], v[190:193], v[26:29]
	v_mfma_f32_16x16x32_bf16 v[22:25], v[146:149], v[198:201], v[22:25]
	v_mfma_f32_16x16x32_bf16 v[18:21], v[174:177], v[198:201], v[18:21]
	v_mfma_f32_16x16x32_bf16 v[14:17], v[146:149], v[218:221], v[14:17]
	v_mfma_f32_16x16x32_bf16 v[10:13], v[174:177], v[218:221], v[10:13]
	v_mfma_f32_16x16x32_bf16 v[38:41], v[150:153], v[186:189], v[38:41]
	v_mfma_f32_16x16x32_bf16 v[34:37], v[178:181], v[186:189], v[34:37]
	v_mfma_f32_16x16x32_bf16 v[30:33], v[150:153], v[194:197], v[30:33]
	v_mfma_f32_16x16x32_bf16 v[26:29], v[178:181], v[194:197], v[26:29]
	v_mfma_f32_16x16x32_bf16 v[22:25], v[150:153], v[214:217], v[22:25]
	v_mfma_f32_16x16x32_bf16 v[18:21], v[178:181], v[214:217], v[18:21]
	v_mfma_f32_16x16x32_bf16 v[14:17], v[150:153], v[222:225], v[14:17]
	v_mfma_f32_16x16x32_bf16 v[10:13], v[178:181], v[222:225], v[10:13]
	s_setprio 0
	s_barrier
	s_add_i32 s75, s75, 2
	s_add_u32 vcc_lo, vcc_lo, 0x100
	s_addc_u32 vcc_hi, vcc_hi, 0
	s_cmp_gt_u32 s75, 41
	s_mov_b64 s[10:11], s[8:9]
	s_cbranch_scc0 .LBB0_806
	s_and_b64 vcc, exec, s[28:29]
	s_cbranch_vccz .LBB0_809
	s_barrier
